# steps-array + folded running-max bias in selected loop, bitwise top-13 threshold search, finer wave rotation, hand-written post-mix norm row loop with hoisted gain vectors
# speedup vs baseline: 1.0680x; 1.0182x over previous
; __device__ __forceinline__ void attention_phase(const Ctx& C) {
;     const int bxx = C.gw / NWAVES; const bool xmode = (C.G & 7) == 0;
;     const int x = bxx & 7, rank = xmode ? (bxx >> 3) * NWAVES + C.wave : C.gw, nrank = xmode ? (C.G >> 3) * NWAVES : C.NGW, nitem = xmode ? 1536 : 12288;
;     const int nper = (nitem + nrank - 1) / nrank, nmem_it = xmode ? (512 + nrank - 1) / nrank : 0; const bool flip = xmode && (nitem % nrank == 0); const int rot = flip ? ((C.wave * 3) >> 3) * 2 : 0;
;     for (int k0 = 0; k0 < nper; ++k0) {
;         const int kk = flip ? (k0 + rot) % nper : k0; const int i = rank + kk * nrank; if (i >= nitem) continue;
.LBB0_646:
	v_readlane_b32 s2, v254, 30
	v_readlane_b32 s3, v254, 31
	s_andn2_b64 vcc, exec, s[2:3]
	s_cbranch_vccnz .LBB0_886
	s_ashr_i32 s2, s1, 6
	s_lshl_b32 s0, s0, 3
	s_add_i32 s3, s0, s2
	s_ashr_i32 s0, s3, 31
	s_lshr_b32 s0, s0, 29
	s_add_i32 s0, s3, s0
	s_mul_i32 s1, s2, 3
	s_ashr_i32 s4, s0, 3
	s_ashr_i32 s1, s1, 2
	s_and_b32 s0, s4, -8
	s_mov_b32 s8, s1
	s_add_i32 s5, s0, s2
	v_readlane_b32 s0, v254, 3
	v_readlane_b32 s1, v254, 4
	s_and_b64 s[0:1], s[0:1], exec
	s_cselect_b32 s9, s5, s3
	s_lshl_b32 s0, s4, 10
	s_and_b32 s0, s0, 0x1800
	s_and_b32 s1, s4, 1
	s_or_b32 s71, s0, s1
	s_lshl_b32 s0, s4, 9
	s_and_b32 s72, s0, 0xe00
	s_addk_i32 s72, 0xfc00
	s_add_u32 s86, s34, 0x10200000
	s_mulk_i32 s2, 0x4100
	s_addc_u32 s87, s35, 0
	s_add_i32 s73, s2, 0
	s_add_u32 s74, s34, 0x3d00000
	s_addc_u32 s75, s35, 0
	s_add_u32 s28, s34, 0x3d80000
	s_addc_u32 s77, s35, 0
	s_add_u32 s90, s34, 0x4200000
	s_addc_u32 s91, s35, 0
	s_add_u32 s94, s34, 0x4a00000
	s_addc_u32 s95, s35, 0
	s_add_u32 s78, s34, 0x3a00000
	s_addc_u32 s79, s35, 0
	s_add_u32 s29, s34, 0x5200000
	s_addc_u32 s37, s35, 0
	s_add_u32 s59, s34, 0x5a00000
	v_and_b32_e32 v252, 63, v0
	s_addc_u32 s80, s35, 0
	s_mov_b32 s96, 0
	s_branch .LBB0_651

; __device__ __forceinline__ void nsa_tile(const Ctx& C, int b, int g, int t0) {
;     ...
;         unsigned key[8][4];
; #pragma unroll
;         for (int q2 = 0; q2 < 8; ++q2)
; #pragma unroll
;             for (int c = 0; c < 4; ++c) { const int j = lane + 64 * c; const bool cand = (j >= 1) && (j < cur - 1); const float v = imp[q2 * 264 + j];
;                 key[q2][c] = cand ? ((__float_as_uint(v) & 0xFFFFFF00u) | (unsigned)(255 - j)) : 0u; }
; #pragma unroll
;         for (int c = 0; c < 4; ++c) bmv[c] = 0u;
; #pragma unroll 1
;         for (int round = 0; round < 13; ++round) {
; #pragma unroll
;             for (int q2 = 0; q2 < 8; ++q2) {
;                 unsigned mx = key[q2][0]; mx = mx > key[q2][1] ? mx : key[q2][1]; mx = mx > key[q2][2] ? mx : key[q2][2]; mx = mx > key[q2][3] ? mx : key[q2][3];
;                 const unsigned w = wave_max_u32(mx);
; #pragma unroll
;                 for (int c = 0; c < 4; ++c) { const bool win = (key[q2][c] == w) && (w != 0u); key[q2][c] = win ? 0u : key[q2][c]; bmv[c] |= win ? (1u << q2) : 0u; }
;             }
;         }
; #pragma unroll
;         for (int c = 0; c < 4; ++c) { const int j = lane + 64 * c; if (j == 0 || j == cur || j == cur - 1) bmv[c] = 0xFFu; }
.LBB0_796:
	s_or_b64 exec, exec, s[2:3]
	v_mov_b32_e32 v37, 0
	s_mov_b32 s2, 13
	v_mov_b32_e32 v40, 0
	v_mov_b32_e32 v39, 0
	v_mov_b32_e32 v38, 0
	s_mov_b32 s16, 0
	s_mov_b32 s17, 0x40000000
.Ltk_iter_0:
	s_or_b32 s4, s16, s17
	v_cmp_le_u32_e64 s[0:1], s4, v3
	v_cmp_le_u32_e64 s[2:3], s4, v2
	v_cmp_le_u32_e64 s[10:11], s4, v8
	v_cmp_le_u32_e32 vcc, s4, v7
	s_bcnt1_i32_b64 s0, s[0:1]
	s_bcnt1_i32_b64 s2, s[2:3]
	s_bcnt1_i32_b64 s10, s[10:11]
	s_bcnt1_i32_b64 s1, vcc
	s_add_i32 s0, s0, s2
	s_add_i32 s1, s1, s10
	s_add_i32 s0, s0, s1
	s_cmp_ge_u32 s0, 13
	s_cselect_b32 s16, s4, s16
	s_cmp_eq_u32 s0, 13
	s_cbranch_scc1 .Ltk_done_0
	s_lshr_b32 s17, s17, 1
	s_cmp_lg_u32 s17, 0
	s_cbranch_scc1 .Ltk_iter_0
.Ltk_done_0:
	v_cmp_le_u32_e64 s[0:1], s16, v3
	v_cmp_le_u32_e64 s[2:3], s16, v2
	v_cmp_le_u32_e64 s[10:11], s16, v8
	v_cmp_le_u32_e32 vcc, s16, v7
	v_cndmask_b32_e64 v41, 0, 1, s[0:1]
	v_cndmask_b32_e64 v42, 0, 1, s[2:3]
	v_cndmask_b32_e64 v43, 0, 1, s[10:11]
	v_cndmask_b32_e64 v44, 0, 1, vcc
	v_or_b32_e32 v37, v37, v41
	v_or_b32_e32 v40, v40, v42
	v_or_b32_e32 v39, v39, v43
	v_or_b32_e32 v38, v38, v44
	s_mov_b32 s16, 0
	s_mov_b32 s17, 0x40000000
.Ltk_iter_1:
	s_or_b32 s4, s16, s17
	v_cmp_le_u32_e64 s[0:1], s4, v10
	v_cmp_le_u32_e64 s[2:3], s4, v9
	v_cmp_le_u32_e64 s[10:11], s4, v12
	v_cmp_le_u32_e32 vcc, s4, v11
	s_bcnt1_i32_b64 s0, s[0:1]
	s_bcnt1_i32_b64 s2, s[2:3]
	s_bcnt1_i32_b64 s10, s[10:11]
	s_bcnt1_i32_b64 s1, vcc
	s_add_i32 s0, s0, s2
	s_add_i32 s1, s1, s10
	s_add_i32 s0, s0, s1
	s_cmp_ge_u32 s0, 13
	s_cselect_b32 s16, s4, s16
	s_cmp_eq_u32 s0, 13
	s_cbranch_scc1 .Ltk_done_1
	s_lshr_b32 s17, s17, 1
	s_cmp_lg_u32 s17, 0
	s_cbranch_scc1 .Ltk_iter_1
.Ltk_done_1:
	v_cmp_le_u32_e64 s[0:1], s16, v10
	v_cmp_le_u32_e64 s[2:3], s16, v9
	v_cmp_le_u32_e64 s[10:11], s16, v12
	v_cmp_le_u32_e32 vcc, s16, v11
	v_cndmask_b32_e64 v41, 0, 2, s[0:1]
	v_cndmask_b32_e64 v42, 0, 2, s[2:3]
	v_cndmask_b32_e64 v43, 0, 2, s[10:11]
	v_cndmask_b32_e64 v44, 0, 2, vcc
	v_or_b32_e32 v37, v37, v41
	v_or_b32_e32 v40, v40, v42
	v_or_b32_e32 v39, v39, v43
	v_or_b32_e32 v38, v38, v44
	s_mov_b32 s16, 0
	s_mov_b32 s17, 0x40000000
.Ltk_iter_2:
	s_or_b32 s4, s16, s17
	v_cmp_le_u32_e64 s[0:1], s4, v14
	v_cmp_le_u32_e64 s[2:3], s4, v13
	v_cmp_le_u32_e64 s[10:11], s4, v16
	v_cmp_le_u32_e32 vcc, s4, v15
	s_bcnt1_i32_b64 s0, s[0:1]
	s_bcnt1_i32_b64 s2, s[2:3]
	s_bcnt1_i32_b64 s10, s[10:11]
	s_bcnt1_i32_b64 s1, vcc
	s_add_i32 s0, s0, s2
	s_add_i32 s1, s1, s10
	s_add_i32 s0, s0, s1
	s_cmp_ge_u32 s0, 13
	s_cselect_b32 s16, s4, s16
	s_cmp_eq_u32 s0, 13
	s_cbranch_scc1 .Ltk_done_2
	s_lshr_b32 s17, s17, 1
	s_cmp_lg_u32 s17, 0
	s_cbranch_scc1 .Ltk_iter_2
.Ltk_done_2:
	v_cmp_le_u32_e64 s[0:1], s16, v14
	v_cmp_le_u32_e64 s[2:3], s16, v13
	v_cmp_le_u32_e64 s[10:11], s16, v16
	v_cmp_le_u32_e32 vcc, s16, v15
	v_cndmask_b32_e64 v41, 0, 4, s[0:1]
	v_cndmask_b32_e64 v42, 0, 4, s[2:3]
	v_cndmask_b32_e64 v43, 0, 4, s[10:11]
	v_cndmask_b32_e64 v44, 0, 4, vcc
	v_or_b32_e32 v37, v37, v41
	v_or_b32_e32 v40, v40, v42
	v_or_b32_e32 v39, v39, v43
	v_or_b32_e32 v38, v38, v44
	s_mov_b32 s16, 0
	s_mov_b32 s17, 0x40000000
.Ltk_iter_3:
	s_or_b32 s4, s16, s17
	v_cmp_le_u32_e64 s[0:1], s4, v18
	v_cmp_le_u32_e64 s[2:3], s4, v17
	v_cmp_le_u32_e64 s[10:11], s4, v20
	v_cmp_le_u32_e32 vcc, s4, v19
	s_bcnt1_i32_b64 s0, s[0:1]
	s_bcnt1_i32_b64 s2, s[2:3]
	s_bcnt1_i32_b64 s10, s[10:11]
	s_bcnt1_i32_b64 s1, vcc
	s_add_i32 s0, s0, s2
	s_add_i32 s1, s1, s10
	s_add_i32 s0, s0, s1
	s_cmp_ge_u32 s0, 13
	s_cselect_b32 s16, s4, s16
	s_cmp_eq_u32 s0, 13
	s_cbranch_scc1 .Ltk_done_3
	s_lshr_b32 s17, s17, 1
	s_cmp_lg_u32 s17, 0
	s_cbranch_scc1 .Ltk_iter_3
.Ltk_done_3:
	v_cmp_le_u32_e64 s[0:1], s16, v18
	v_cmp_le_u32_e64 s[2:3], s16, v17
	v_cmp_le_u32_e64 s[10:11], s16, v20
	v_cmp_le_u32_e32 vcc, s16, v19
	v_cndmask_b32_e64 v41, 0, 8, s[0:1]
	v_cndmask_b32_e64 v42, 0, 8, s[2:3]
	v_cndmask_b32_e64 v43, 0, 8, s[10:11]
	v_cndmask_b32_e64 v44, 0, 8, vcc
	v_or_b32_e32 v37, v37, v41
	v_or_b32_e32 v40, v40, v42
	v_or_b32_e32 v39, v39, v43
	v_or_b32_e32 v38, v38, v44
	s_mov_b32 s16, 0
	s_mov_b32 s17, 0x40000000
.Ltk_iter_4:
	s_or_b32 s4, s16, s17
	v_cmp_le_u32_e64 s[0:1], s4, v22
	v_cmp_le_u32_e64 s[2:3], s4, v21
	v_cmp_le_u32_e64 s[10:11], s4, v24
	v_cmp_le_u32_e32 vcc, s4, v23
	s_bcnt1_i32_b64 s0, s[0:1]
	s_bcnt1_i32_b64 s2, s[2:3]
	s_bcnt1_i32_b64 s10, s[10:11]
	s_bcnt1_i32_b64 s1, vcc
	s_add_i32 s0, s0, s2
	s_add_i32 s1, s1, s10
	s_add_i32 s0, s0, s1
	s_cmp_ge_u32 s0, 13
	s_cselect_b32 s16, s4, s16
	s_cmp_eq_u32 s0, 13
	s_cbranch_scc1 .Ltk_done_4
	s_lshr_b32 s17, s17, 1
	s_cmp_lg_u32 s17, 0
	s_cbranch_scc1 .Ltk_iter_4
; __device__ __forceinline__ void nsa_tile(const Ctx& C, int b, int g, int t0) {
;     ...
; #pragma unroll 1
;         for (int round = 0; round < 13; ++round) {
; #pragma unroll
;             for (int q2 = 0; q2 < 8; ++q2) {
;                 unsigned mx = key[q2][0]; mx = mx > key[q2][1] ? mx : key[q2][1]; mx = mx > key[q2][2] ? mx : key[q2][2]; mx = mx > key[q2][3] ? mx : key[q2][3];
;                 const unsigned w = wave_max_u32(mx);
; #pragma unroll
;                 for (int c = 0; c < 4; ++c) { const bool win = (key[q2][c] == w) && (w != 0u); key[q2][c] = win ? 0u : key[q2][c]; bmv[c] |= win ? (1u << q2) : 0u; }
;             }
;         }
; #pragma unroll
;         for (int c = 0; c < 4; ++c) { const int j = lane + 64 * c; if (j == 0 || j == cur || j == cur - 1) bmv[c] = 0xFFu; }
.Ltk_done_4:
	v_cmp_le_u32_e64 s[0:1], s16, v22
	v_cmp_le_u32_e64 s[2:3], s16, v21
	v_cmp_le_u32_e64 s[10:11], s16, v24
	v_cmp_le_u32_e32 vcc, s16, v23
	v_cndmask_b32_e64 v41, 0, 16, s[0:1]
	v_cndmask_b32_e64 v42, 0, 16, s[2:3]
	v_cndmask_b32_e64 v43, 0, 16, s[10:11]
	v_cndmask_b32_e64 v44, 0, 16, vcc
	v_or_b32_e32 v37, v37, v41
	v_or_b32_e32 v40, v40, v42
	v_or_b32_e32 v39, v39, v43
	v_or_b32_e32 v38, v38, v44
	s_mov_b32 s16, 0
	s_mov_b32 s17, 0x40000000
.Ltk_iter_5:
	s_or_b32 s4, s16, s17
	v_cmp_le_u32_e64 s[0:1], s4, v26
	v_cmp_le_u32_e64 s[2:3], s4, v25
	v_cmp_le_u32_e64 s[10:11], s4, v28
	v_cmp_le_u32_e32 vcc, s4, v27
	s_bcnt1_i32_b64 s0, s[0:1]
	s_bcnt1_i32_b64 s2, s[2:3]
	s_bcnt1_i32_b64 s10, s[10:11]
	s_bcnt1_i32_b64 s1, vcc
	s_add_i32 s0, s0, s2
	s_add_i32 s1, s1, s10
	s_add_i32 s0, s0, s1
	s_cmp_ge_u32 s0, 13
	s_cselect_b32 s16, s4, s16
	s_cmp_eq_u32 s0, 13
	s_cbranch_scc1 .Ltk_done_5
	s_lshr_b32 s17, s17, 1
	s_cmp_lg_u32 s17, 0
	s_cbranch_scc1 .Ltk_iter_5
.Ltk_done_5:
	v_cmp_le_u32_e64 s[0:1], s16, v26
	v_cmp_le_u32_e64 s[2:3], s16, v25
	v_cmp_le_u32_e64 s[10:11], s16, v28
	v_cmp_le_u32_e32 vcc, s16, v27
	v_cndmask_b32_e64 v41, 0, 32, s[0:1]
	v_cndmask_b32_e64 v42, 0, 32, s[2:3]
	v_cndmask_b32_e64 v43, 0, 32, s[10:11]
	v_cndmask_b32_e64 v44, 0, 32, vcc
	v_or_b32_e32 v37, v37, v41
	v_or_b32_e32 v40, v40, v42
	v_or_b32_e32 v39, v39, v43
	v_or_b32_e32 v38, v38, v44
	s_mov_b32 s16, 0
	s_mov_b32 s17, 0x40000000
.Ltk_iter_6:
	s_or_b32 s4, s16, s17
	v_cmp_le_u32_e64 s[0:1], s4, v30
	v_cmp_le_u32_e64 s[2:3], s4, v29
	v_cmp_le_u32_e64 s[10:11], s4, v32
	v_cmp_le_u32_e32 vcc, s4, v31
	s_bcnt1_i32_b64 s0, s[0:1]
	s_bcnt1_i32_b64 s2, s[2:3]
	s_bcnt1_i32_b64 s10, s[10:11]
	s_bcnt1_i32_b64 s1, vcc
	s_add_i32 s0, s0, s2
	s_add_i32 s1, s1, s10
	s_add_i32 s0, s0, s1
	s_cmp_ge_u32 s0, 13
	s_cselect_b32 s16, s4, s16
	s_cmp_eq_u32 s0, 13
	s_cbranch_scc1 .Ltk_done_6
	s_lshr_b32 s17, s17, 1
	s_cmp_lg_u32 s17, 0
	s_cbranch_scc1 .Ltk_iter_6
.Ltk_done_6:
	v_cmp_le_u32_e64 s[0:1], s16, v30
	v_cmp_le_u32_e64 s[2:3], s16, v29
	v_cmp_le_u32_e64 s[10:11], s16, v32
	v_cmp_le_u32_e32 vcc, s16, v31
	v_cndmask_b32_e64 v41, 0, 64, s[0:1]
	v_cndmask_b32_e64 v42, 0, 64, s[2:3]
	v_cndmask_b32_e64 v43, 0, 64, s[10:11]
	v_cndmask_b32_e64 v44, 0, 64, vcc
	v_or_b32_e32 v37, v37, v41
	v_or_b32_e32 v40, v40, v42
	v_or_b32_e32 v39, v39, v43
	v_or_b32_e32 v38, v38, v44
	s_mov_b32 s16, 0
	s_mov_b32 s17, 0x40000000
.Ltk_iter_7:
	s_or_b32 s4, s16, s17
	v_cmp_le_u32_e64 s[0:1], s4, v34
	v_cmp_le_u32_e64 s[2:3], s4, v33
	v_cmp_le_u32_e64 s[10:11], s4, v36
	v_cmp_le_u32_e32 vcc, s4, v35
	s_bcnt1_i32_b64 s0, s[0:1]
	s_bcnt1_i32_b64 s2, s[2:3]
	s_bcnt1_i32_b64 s10, s[10:11]
	s_bcnt1_i32_b64 s1, vcc
	s_add_i32 s0, s0, s2
	s_add_i32 s1, s1, s10
	s_add_i32 s0, s0, s1
	s_cmp_ge_u32 s0, 13
	s_cselect_b32 s16, s4, s16
	s_cmp_eq_u32 s0, 13
	s_cbranch_scc1 .Ltk_done_7
	s_lshr_b32 s17, s17, 1
	s_cmp_lg_u32 s17, 0
	s_cbranch_scc1 .Ltk_iter_7
.Ltk_done_7:
	v_cmp_le_u32_e64 s[0:1], s16, v34
	v_cmp_le_u32_e64 s[2:3], s16, v33
	v_cmp_le_u32_e64 s[10:11], s16, v36
	v_cmp_le_u32_e32 vcc, s16, v35
	v_cndmask_b32_e64 v41, 0, v250, s[0:1]
	v_cndmask_b32_e64 v42, 0, v250, s[2:3]
	v_cndmask_b32_e64 v43, 0, v250, s[10:11]
	v_cndmask_b32_e64 v44, 0, v250, vcc
	v_or_b32_e32 v37, v37, v41
	v_or_b32_e32 v40, v40, v42
	v_or_b32_e32 v39, v39, v43
	v_or_b32_e32 v38, v38, v44
	v_cmp_eq_u32_e32 vcc, 0, v224
	v_cmp_eq_u32_e64 s[0:1], s6, v224
	s_or_b64 s[0:1], vcc, s[0:1]
	v_cmp_eq_u32_e32 vcc, s24, v224
	s_or_b64 vcc, s[0:1], vcc
	v_mov_b32_e32 v2, 0xff
	v_cndmask_b32_e32 v8, v37, v2, vcc
	v_cmp_eq_u32_e32 vcc, 0, v4
	v_cmp_eq_u32_e64 s[0:1], s6, v4
	s_or_b64 s[0:1], vcc, s[0:1]
	v_cmp_eq_u32_e32 vcc, s24, v4
	s_or_b64 vcc, s[0:1], vcc
	v_cmp_eq_u32_e64 s[0:1], s6, v5
	v_cndmask_b32_e32 v7, v40, v2, vcc
	v_cmp_eq_u32_e32 vcc, 0, v5
	s_or_b64 s[0:1], vcc, s[0:1]
	v_cmp_eq_u32_e32 vcc, s24, v5
	s_or_b64 vcc, s[0:1], vcc
	v_cmp_eq_u32_e64 s[0:1], s6, v6
	v_cndmask_b32_e32 v3, v39, v2, vcc
	v_cmp_eq_u32_e32 vcc, 0, v6
	s_or_b64 s[0:1], vcc, s[0:1]
	v_cmp_eq_u32_e32 vcc, s24, v6
	s_or_b64 vcc, s[0:1], vcc
	s_mov_b64 s[0:1], 0
	v_cndmask_b32_e32 v2, v38, v2, vcc

; __device__ __forceinline__ float bf_lo(unsigned u) { return __uint_as_float(u << 16); }
; __device__ __forceinline__ float bf_hi(unsigned u) { return __uint_as_float(u & 0xffff0000u); }
; __device__ __forceinline__ float bf1(bf16_t u) { return __uint_as_float(((unsigned)u) << 16); }
; __device__ __forceinline__ float sigm(float x) { return rcpf_(1.f + ex2(-1.44269504f * x)); }
; __device__ __forceinline__ bf16x8 pack_p(const float* p) { u32x4 w; w.x = cvt_pk_bf16(p[0], p[1]); w.y = cvt_pk_bf16(p[2], p[3]); w.z = cvt_pk_bf16(p[4], p[5]); w.w = cvt_pk_bf16(p[6], p[7]); return __builtin_bit_cast(bf16x8, w); }
; __device__ __forceinline__ void nsa_tile(const Ctx& C, int b, int g, int t0) {
;     ...
;         const int tq = t0 + qi4;
;         bf16x8 q16f[2][2]; float gs4[2];
; #pragma unroll
;         for (int sub = 0; sub < 2; ++sub) {
;             const size_t tok4 = (size_t)b * S_ + tq + 4 * sub;
;             const bf16_t* qp = P + tok4 * PP + PC_Q + head4 * 64;
;             q16f[sub][1] = scale_q(*(const u32x4*)(qp + 32 + 8 * fq), QS);
;             const u32x4 mv4 = *(const u32x4*)(qp + 8 * fq), pv4 = *(const u32x4*)(qp + 8 * ((fq ^ 1) & 1));
;             const float* rt = (const float*)(C.ws + WS_ROPE) + tok4 * 16;
;             const f32x4 ca = *(const f32x4*)rt, cb2 = *(const f32x4*)(rt + 4), sa = *(const f32x4*)(rt + 8), sb = *(const f32x4*)(rt + 12);
;             const float cs[8] = {ca.x, ca.y, ca.z, ca.w, cb2.x, cb2.y, cb2.z, cb2.w}, sn[8] = {sa.x, sa.y, sa.z, sa.w, sb.x, sb.y, sb.z, sb.w};
;             const float mv[8] = {bf_lo(mv4.x), bf_hi(mv4.x), bf_lo(mv4.y), bf_hi(mv4.y), bf_lo(mv4.z), bf_hi(mv4.z), bf_lo(mv4.w), bf_hi(mv4.w)};
;             const float pp[8] = {bf_lo(pv4.x), bf_hi(pv4.x), bf_lo(pv4.y), bf_hi(pv4.y), bf_lo(pv4.z), bf_hi(pv4.z), bf_lo(pv4.w), bf_hi(pv4.w)};
;             const bool roped = fq < 2; const float sg = (fq == 0) ? -1.f : 1.f; float o[8];
; #pragma unroll
;             for (int e = 0; e < 8; ++e) o[e] = (roped ? (mv[e] * cs[e] + sg * pp[e] * sn[e]) : mv[e]) * QS;
;             q16f[sub][0] = pack_p(o);
;             gs4[sub] = sigm(bf1(P[tok4 * PP + PC_NG + head4 * 3 + 1]));
.LBB0_809:
	s_or_b64 exec, exec, s[0:1]
	v_bfe_u32 v12, v224, 2, 2
	v_or_b32_e32 v211, s97, v12
	v_or_b32_e32 v10, s76, v211
	v_mov_b64_e32 v[2:3], s[86:87]
	v_mad_u64_u32 v[4:5], s[0:1], v10, s67, v[2:3]
	v_mov_b32_e32 v179, v1
	v_lshl_add_u64 v[6:7], v[4:5], 0, v[178:179]
	s_bcnt1_i32_b64 s2, vcc
	v_add_co_u32_e32 v6, vcc, 0x1000, v6
	s_waitcnt lgkmcnt(0)
	s_add_i32 s3, s3, s2
	s_nop 0
	v_addc_co_u32_e32 v7, vcc, 0, v7, vcc
	global_load_ushort v251, v[6:7], off offset:2562
	v_or_b32_e32 v6, 4, v10
	v_mad_u64_u32 v[2:3], s[0:1], v6, s67, v[2:3]
	v_lshl_add_u64 v[8:9], v[2:3], 0, v[178:179]
	v_add_co_u32_e32 v8, vcc, 0x1000, v8
	v_mov_b64_e32 v[246:247], 0x200
	s_nop 0
	v_addc_co_u32_e32 v9, vcc, 0, v9, vcc
	global_load_ushort v210, v[8:9], off offset:2562
	v_mov_b64_e32 v[216:217], 0xaff
	v_ashrrev_i32_e32 v245, 4, v224
	s_cmp_eq_u32 s3, 0
	v_lshlrev_b64 v[228:229], 4, v[224:225]
	v_lshlrev_b32_e32 v226, 1, v186
	s_cbranch_scc1 .LBB0_865
	v_lshlrev_b32_e32 v232, 3, v245
	v_ashrrev_i32_e32 v233, 31, v232
	v_mov_b32_e32 v227, v1
	v_lshl_add_u64 v[18:19], v[4:5], 0, v[226:227]
	v_lshlrev_b64 v[4:5], 1, v[232:233]
	v_lshl_add_u64 v[8:9], v[18:19], 0, v[4:5]
	global_load_dwordx4 v[14:17], v[8:9], off offset:3136
	v_bitop3_b32 v13, v232, 8, v232 bitop3:0xc
	v_mov_b32_e32 v11, v1
	v_lshlrev_b64 v[10:11], 6, v[10:11]
	v_lshl_add_u64 v[10:11], s[78:79], 0, v[10:11]
	s_lshl_b64 s[0:1], s[22:23], 4
	s_add_u32 s10, s90, s0
	s_addc_u32 s11, s91, s1
	s_add_u32 s4, s94, s0
	s_addc_u32 s5, s95, s1
	v_cmp_gt_u32_e64 s[0:1], 16, v224
	v_cmp_gt_i32_e32 vcc, 2, v245
	v_mov_b32_e32 v7, v1
	v_lshlrev_b64 v[6:7], 6, v[6:7]
	v_lshl_add_u64 v[6:7], s[78:79], 0, v[6:7]
	v_lshl_add_u64 v[234:235], s[4:5], 0, v[228:229]
	v_lshl_add_u64 v[230:231], s[10:11], 0, v[228:229]
	s_lshl_b32 s3, s3, 1
	s_mov_b32 s2, 4
	s_add_i32 s18, s3, -1
	s_waitcnt vmcnt(0)
	v_lshlrev_b32_e32 v20, 16, v14
	v_and_b32_e32 v21, 0xffff0000, v14
	v_lshlrev_b32_e32 v14, 16, v15
	v_and_b32_e32 v15, 0xffff0000, v15
	v_pk_mul_f32 v[14:15], v[14:15], s[38:39] op_sel_hi:[1,0]
	v_pk_mul_f32 v[20:21], v[20:21], s[38:39] op_sel_hi:[1,0]
	v_cvt_pk_bf16_f32 v99, v14, v15
	v_lshlrev_b32_e32 v14, 16, v16
	v_and_b32_e32 v15, 0xffff0000, v16
	v_pk_mul_f32 v[14:15], v[14:15], s[38:39] op_sel_hi:[1,0]
	v_cvt_pk_bf16_f32 v98, v20, v21
	v_cvt_pk_bf16_f32 v100, v14, v15
	v_lshlrev_b32_e32 v14, 16, v17
	v_and_b32_e32 v15, 0xffff0000, v17
	v_pk_mul_f32 v[14:15], v[14:15], s[38:39] op_sel_hi:[1,0]
	s_nop 0
	v_cvt_pk_bf16_f32 v101, v14, v15
	global_load_dwordx4 v[14:17], v[8:9], off offset:3072
	v_lshlrev_b32_e32 v8, 1, v13
	v_mov_b32_e32 v9, v1
	v_lshl_add_u64 v[18:19], v[18:19], 0, v[8:9]
	global_load_dwordx4 v[18:21], v[18:19], off offset:3072
	s_nop 0
	global_load_dwordx4 v[22:25], v[10:11], off offset:16
	global_load_dwordx4 v[26:29], v[10:11], off offset:48
	global_load_dwordx4 v[30:33], v[10:11], off
	global_load_dwordx4 v[34:37], v[10:11], off offset:32
	s_waitcnt vmcnt(5)
	v_lshlrev_b32_e32 v10, 16, v14
	v_lshlrev_b32_e32 v44, 16, v17
	v_and_b32_e32 v46, 0xffff0000, v17
	v_and_b32_e32 v14, 0xffff0000, v14
	s_waitcnt vmcnt(4)
	v_lshlrev_b32_e32 v11, 16, v18
	v_and_b32_e32 v13, 0xffff0000, v18
	v_lshlrev_b32_e32 v17, 16, v19
	v_and_b32_e32 v41, 0xffff0000, v19
	v_cndmask_b32_e64 v11, v11, -v11, s[0:1]
	s_waitcnt vmcnt(1)
	v_mov_b32_e32 v18, v30
	s_waitcnt vmcnt(0)
	v_mov_b32_e32 v19, v34
	v_pk_mul_f32 v[18:19], v[18:19], v[10:11]
	v_lshlrev_b32_e32 v38, 16, v15
	v_add_f32_e32 v11, v18, v19
	v_and_b32_e32 v40, 0xffff0000, v15
	v_cndmask_b32_e32 v10, v10, v11, vcc
	v_cndmask_b32_e64 v15, v13, -v13, s[0:1]
	v_mov_b32_e32 v34, v31
	v_mul_f32_e32 v18, 0x3e38aa3b, v10
	v_pk_mul_f32 v[10:11], v[34:35], v[14:15]
	v_cndmask_b32_e64 v39, v17, -v17, s[0:1]
	v_add_f32_e32 v10, v10, v11
	v_cndmask_b32_e32 v10, v14, v10, vcc
	v_mul_f32_e32 v13, 0x3e38aa3b, v10
	v_mov_b32_e32 v10, v32
	v_mov_b32_e32 v11, v36
	v_pk_mul_f32 v[10:11], v[10:11], v[38:39]
	v_cndmask_b32_e64 v41, v41, -v41, s[0:1]
	v_add_f32_e32 v10, v10, v11
	v_cndmask_b32_e32 v10, v38, v10, vcc
	v_mov_b32_e32 v36, v33
	v_mul_f32_e32 v14, 0x3e38aa3b, v10
	v_pk_mul_f32 v[10:11], v[36:37], v[40:41]
	v_lshlrev_b32_e32 v43, 16, v20
	v_add_f32_e32 v10, v10, v11
	v_cndmask_b32_e32 v10, v40, v10, vcc
	v_lshlrev_b32_e32 v42, 16, v16
	v_mul_f32_e32 v15, 0x3e38aa3b, v10
	v_cndmask_b32_e64 v43, v43, -v43, s[0:1]
	v_mov_b32_e32 v10, v22
	v_mov_b32_e32 v11, v26
	v_pk_mul_f32 v[10:11], v[10:11], v[42:43]
	v_and_b32_e32 v20, 0xffff0000, v20
	v_add_f32_e32 v10, v10, v11
	v_and_b32_e32 v16, 0xffff0000, v16
	v_cndmask_b32_e32 v10, v42, v10, vcc
	v_cndmask_b32_e64 v17, v20, -v20, s[0:1]
	v_mov_b32_e32 v26, v23
	v_mul_f32_e32 v19, 0x3e38aa3b, v10
	v_pk_mul_f32 v[10:11], v[26:27], v[16:17]
	v_lshlrev_b32_e32 v45, 16, v21
	v_add_f32_e32 v10, v10, v11
	v_cndmask_b32_e32 v10, v16, v10, vcc
	v_mul_f32_e32 v16, 0x3e38aa3b, v10
	v_cndmask_b32_e64 v45, v45, -v45, s[0:1]
	v_mov_b32_e32 v10, v24
	v_mov_b32_e32 v11, v28
	v_pk_mul_f32 v[10:11], v[10:11], v[44:45]
	v_and_b32_e32 v21, 0xffff0000, v21
	v_add_f32_e32 v10, v10, v11
	v_cndmask_b32_e32 v10, v44, v10, vcc
	v_cndmask_b32_e64 v47, v21, -v21, s[0:1]
	v_mov_b32_e32 v28, v25
	v_mul_f32_e32 v17, 0x3e38aa3b, v10
	v_pk_mul_f32 v[10:11], v[28:29], v[46:47]
	v_cvt_pk_bf16_f32 v103, v14, v15
	v_add_f32_e32 v10, v10, v11
	v_cndmask_b32_e32 v10, v46, v10, vcc
	v_mul_f32_e32 v10, 0x3e38aa3b, v10
	v_cvt_pk_bf16_f32 v105, v17, v10
	v_lshl_add_u64 v[10:11], v[2:3], 0, v[226:227]
	v_lshl_add_u64 v[14:15], v[10:11], 0, v[4:5]
	global_load_dwordx4 v[2:5], v[14:15], off offset:3136
	v_cvt_pk_bf16_f32 v104, v19, v16
	v_lshl_add_u64 v[8:9], v[10:11], 0, v[8:9]
	v_cvt_pk_bf16_f32 v102, v18, v13
	global_load_dwordx4 v[8:11], v[8:9], off offset:3072
	s_waitcnt vmcnt(1)
; #define LAS __attribute__((address_space(3)))
; __device__ __forceinline__ unsigned flash16_entry(int s, const LAS unsigned* list) {
;     const unsigned e = (unsigned)__builtin_amdgcn_readfirstlane((int)list[s >> 1]);
;     return (e & 0xffff0000u) | (2u * (e & 0xffffu) + (unsigned)(s & 1));
; }
; __device__ __forceinline__ void flash16_run(const bf16x8* kb, const bf16x8* vb, const bf16x8 (&qa)[2], const bf16x8 (&qb)[2], int nsteps, const LAS unsigned* list, int tq, int t0, int qi4, int fq, ...
;     if (nsteps <= 0) return;
;     bf16x8 kA[4], vA[4], kB[4], vB[4], kC[4], vC[4]; unsigned eA, eB, eC;
;     ...
;     F16_LOAD(0, kA, vA, eA); F16_LOAD(1, kB, vB, eB);
; __device__ __forceinline__ void nsa_tile(const Ctx& C, int b, int g, int t0) {
;     ...
;         for (int sub = 0; sub < 2; ++sub) {
;             const size_t tok4 = (size_t)b * S_ + tq + 4 * sub;
;             const bf16_t* qp = P + tok4 * PP + PC_Q + head4 * 64;
;             q16f[sub][1] = scale_q(*(const u32x4*)(qp + 32 + 8 * fq), QS);
;             const u32x4 mv4 = *(const u32x4*)(qp + 8 * fq), pv4 = *(const u32x4*)(qp + 8 * ((fq ^ 1) & 1));
;             const float* rt = (const float*)(C.ws + WS_ROPE) + tok4 * 16;
;             const f32x4 ca = *(const f32x4*)rt, cb2 = *(const f32x4*)(rt + 4), sa = *(const f32x4*)(rt + 8), sb = *(const f32x4*)(rt + 12);
;             const float cs[8] = {ca.x, ca.y, ca.z, ca.w, cb2.x, cb2.y, cb2.z, cb2.w}, sn[8] = {sa.x, sa.y, sa.z, sa.w, sb.x, sb.y, sb.z, sb.w};
;             const float mv[8] = {bf_lo(mv4.x), bf_hi(mv4.x), bf_lo(mv4.y), bf_hi(mv4.y), bf_lo(mv4.z), bf_hi(mv4.z), bf_lo(mv4.w), bf_hi(mv4.w)};
;             const float pp[8] = {bf_lo(pv4.x), bf_hi(pv4.x), bf_lo(pv4.y), bf_hi(pv4.y), bf_lo(pv4.z), bf_hi(pv4.z), bf_lo(pv4.w), bf_hi(pv4.w)};
;             const bool roped = fq < 2; const float sg = (fq == 0) ? -1.f : 1.f; float o[8];
; #pragma unroll
;             for (int e = 0; e < 8; ++e) o[e] = (roped ? (mv[e] * cs[e] + sg * pp[e] * sn[e]) : mv[e]) * QS;
;             q16f[sub][0] = pack_p(o);
;             gs4[sub] = sigm(bf1(P[tok4 * PP + PC_NG + head4 * 3 + 1]));
;         }
;         float ma = -1e30f, la = 0.f, mb = -1e30f, lb = 0.f; f32x4v Oa[4], Ob[4];
; #pragma unroll
;         for (int dt = 0; dt < 4; ++dt) { Oa[dt] = (f32x4v){0.f, 0.f, 0.f, 0.f}; Ob[dt] = (f32x4v){0.f, 0.f, 0.f, 0.f}; }
	v_lshlrev_b32_e32 v16, 16, v2
	v_and_b32_e32 v17, 0xffff0000, v2
	v_lshlrev_b32_e32 v2, 16, v3
	v_and_b32_e32 v3, 0xffff0000, v3
	v_pk_mul_f32 v[2:3], v[2:3], s[38:39] op_sel_hi:[1,0]
	v_pk_mul_f32 v[16:17], v[16:17], s[38:39] op_sel_hi:[1,0]
	v_cvt_pk_bf16_f32 v107, v2, v3
	v_lshlrev_b32_e32 v2, 16, v4
	v_and_b32_e32 v3, 0xffff0000, v4
	v_pk_mul_f32 v[2:3], v[2:3], s[38:39] op_sel_hi:[1,0]
	v_cvt_pk_bf16_f32 v106, v16, v17
	v_cvt_pk_bf16_f32 v108, v2, v3
	v_lshlrev_b32_e32 v2, 16, v5
	v_and_b32_e32 v3, 0xffff0000, v5
	v_pk_mul_f32 v[2:3], v[2:3], s[38:39] op_sel_hi:[1,0]
	s_waitcnt vmcnt(0)
	v_and_b32_e32 v13, 0xffff0000, v9
	v_cvt_pk_bf16_f32 v109, v2, v3
	global_load_dwordx4 v[2:5], v[14:15], off offset:3072
	s_nop 0
	global_load_dwordx4 v[14:17], v[6:7], off offset:16
	global_load_dwordx4 v[18:21], v[6:7], off offset:48
	global_load_dwordx4 v[22:25], v[6:7], off
	global_load_dwordx4 v[26:29], v[6:7], off offset:32
	v_lshlrev_b32_e32 v7, 16, v8
	v_lshlrev_b32_e32 v35, 16, v10
	v_and_b32_e32 v10, 0xffff0000, v10
	v_lshlrev_b32_e32 v37, 16, v11
	v_and_b32_e32 v11, 0xffff0000, v11
	v_cndmask_b32_e64 v7, v7, -v7, s[0:1]
	v_cndmask_b32_e64 v33, v13, -v13, s[0:1]
	v_cndmask_b32_e64 v35, v35, -v35, s[0:1]
	v_cndmask_b32_e64 v37, v37, -v37, s[0:1]
	v_cndmask_b32_e64 v39, v11, -v11, s[0:1]
	s_waitcnt vmcnt(4)
	v_lshlrev_b32_e32 v6, 16, v2
	v_lshlrev_b32_e32 v30, 16, v3
	v_and_b32_e32 v32, 0xffff0000, v3
	v_lshlrev_b32_e32 v36, 16, v5
	v_and_b32_e32 v38, 0xffff0000, v5
	v_and_b32_e32 v3, 0xffff0000, v8
	v_lshlrev_b32_e32 v5, 16, v9
	s_waitcnt vmcnt(1)
	v_mov_b32_e32 v8, v22
	s_waitcnt vmcnt(0)
	v_mov_b32_e32 v9, v26
	v_pk_mul_f32 v[8:9], v[8:9], v[6:7]
	v_and_b32_e32 v2, 0xffff0000, v2
	v_add_f32_e32 v7, v8, v9
	v_cndmask_b32_e32 v6, v6, v7, vcc
	v_cndmask_b32_e64 v3, v3, -v3, s[0:1]
	v_mov_b32_e32 v26, v23
	v_mul_f32_e32 v8, 0x3e38aa3b, v6
	v_pk_mul_f32 v[6:7], v[26:27], v[2:3]
	v_cndmask_b32_e64 v31, v5, -v5, s[0:1]
	v_add_f32_e32 v3, v6, v7
	v_cndmask_b32_e32 v2, v2, v3, vcc
	v_mul_f32_e32 v6, 0x3e38aa3b, v2
	v_mov_b32_e32 v2, v24
	v_mov_b32_e32 v3, v28
	v_pk_mul_f32 v[2:3], v[2:3], v[30:31]
	v_mov_b32_e32 v28, v25
	v_add_f32_e32 v2, v2, v3
	v_cndmask_b32_e32 v2, v30, v2, vcc
	v_mul_f32_e32 v7, 0x3e38aa3b, v2
	v_pk_mul_f32 v[2:3], v[28:29], v[32:33]
	v_lshlrev_b32_e32 v34, 16, v4
	v_add_f32_e32 v2, v2, v3
	v_cndmask_b32_e32 v2, v32, v2, vcc
	v_mul_f32_e32 v9, 0x3e38aa3b, v2
	v_mov_b32_e32 v2, v14
	v_mov_b32_e32 v3, v18
	v_pk_mul_f32 v[2:3], v[2:3], v[34:35]
	v_and_b32_e32 v4, 0xffff0000, v4
	v_add_f32_e32 v2, v2, v3
	v_cndmask_b32_e32 v2, v34, v2, vcc
	v_cndmask_b32_e64 v5, v10, -v10, s[0:1]
	v_mov_b32_e32 v18, v15
	v_mul_f32_e32 v13, 0x3e38aa3b, v2
	v_pk_mul_f32 v[2:3], v[18:19], v[4:5]
	v_cvt_pk_bf16_f32 v110, v8, v6
	v_add_f32_e32 v2, v2, v3
	v_cndmask_b32_e32 v2, v4, v2, vcc
	v_mul_f32_e32 v4, 0x3e38aa3b, v2
	v_mov_b32_e32 v2, v16
	v_mov_b32_e32 v3, v20
	v_pk_mul_f32 v[2:3], v[2:3], v[36:37]
	v_mov_b32_e32 v20, v17
	v_add_f32_e32 v2, v2, v3
	v_cndmask_b32_e32 v2, v36, v2, vcc
	v_mul_f32_e32 v5, 0x3e38aa3b, v2
	v_pk_mul_f32 v[2:3], v[20:21], v[38:39]
	v_mov_b32_e32 v6, s73
	v_add_f32_e32 v2, v2, v3
	v_cndmask_b32_e32 v2, v38, v2, vcc
	v_mul_f32_e32 v2, 0x3e38aa3b, v2
	v_cvt_pk_bf16_f32 v113, v5, v2
	v_cvt_pk_bf16_f32 v112, v13, v4
	v_cvt_pk_bf16_f32 v111, v7, v9
	v_lshlrev_b32_e64 v225, v12, 1
	v_or_b32_e32 v227, 4, v211
	s_lshr_b32 s0, s3, 1
	s_add_i32 s0, s0, -1
	s_add_i32 s1, s73, 0x400
	v_mov_b32_e32 v6, 0x8000
	v_mov_b32_e32 v14, v224
	v_min_u32_e32 v2, s0, v14
	v_lshl_add_u32 v2, v2, 2, s73
	ds_read_b32 v16, v2
	v_add_u32_e32 v15, 64, v224
	v_min_u32_e32 v3, s0, v15
	v_lshl_add_u32 v3, v3, 2, s73
	ds_read_b32 v17, v3
	s_waitcnt lgkmcnt(0)
	v_and_b32_e32 v2, 0xffff, v16
	v_lshlrev_b32_e32 v2, 1, v2
	v_and_b32_e32 v3, 0xffff0000, v16
	v_or_b32_e32 v3, v3, v2
	v_lshl_add_u32 v4, v2, 5, 31
	v_cmp_ge_u32_e32 vcc, s97, v4
	v_add_u32_e32 v4, 32, v4
	v_cndmask_b32_e32 v5, 0, v6, vcc
	v_cmp_ge_u32_e32 vcc, s97, v4
	v_or_b32_e32 v8, v3, v5
	v_lshl_add_u32 v7, v14, 3, s1
	v_cndmask_b32_e32 v5, 0, v6, vcc
	v_or3_b32 v9, v3, v5, 1
	ds_write_b64 v7, v[8:9]
	v_and_b32_e32 v2, 0xffff, v17
	v_lshlrev_b32_e32 v2, 1, v2
	v_and_b32_e32 v3, 0xffff0000, v17
	v_or_b32_e32 v3, v3, v2
	v_lshl_add_u32 v4, v2, 5, 31
	v_cmp_ge_u32_e32 vcc, s97, v4
	v_add_u32_e32 v4, 32, v4
	v_cndmask_b32_e32 v5, 0, v6, vcc
	v_cmp_ge_u32_e32 vcc, s97, v4
	v_or_b32_e32 v8, v3, v5
	v_lshl_add_u32 v7, v15, 3, s1
	v_cndmask_b32_e32 v5, 0, v6, vcc
	v_or3_b32 v9, v3, v5, 1
	ds_write_b64 v7, v[8:9]
	v_mov_b32_e32 v18, v1
	v_mov_b32_e32 v19, v1
	v_mov_b32_e32 v20, v1
	v_mov_b32_e32 v21, v1
	v_mov_b32_e32 v22, v1
	v_mov_b32_e32 v23, v1
	v_mov_b32_e32 v24, v1
	v_mov_b32_e32 v25, v1
	v_mov_b32_e32 v26, v1
	v_mov_b32_e32 v27, v1
	v_mov_b32_e32 v28, v1
	v_mov_b32_e32 v29, v1
	v_mov_b32_e32 v30, v1
	v_mov_b32_e32 v31, v1
	v_mov_b32_e32 v32, v1
	v_mov_b32_e32 v33, v1
	v_mov_b32_e32 v34, v1
	v_mov_b32_e32 v35, v1
	v_mov_b32_e32 v36, v1
	v_mov_b32_e32 v37, v1
	v_mov_b32_e32 v38, v1
	v_mov_b32_e32 v39, v1
	v_mov_b32_e32 v40, v1
	v_mov_b32_e32 v41, v1
	v_mov_b32_e32 v42, v1
	v_mov_b32_e32 v43, v1
	v_mov_b32_e32 v44, v1
	v_mov_b32_e32 v45, v1
	v_mov_b32_e32 v46, v1
	v_mov_b32_e32 v47, v1
	v_mov_b32_e32 v48, v1
	v_mov_b32_e32 v49, v1
	v_mov_b32_e32 v236, v249
	v_mov_b32_e32 v237, v249
	v_mov_b32_e32 v94, v249
	v_mov_b32_e32 v95, v249
	v_mov_b32_e32 v96, 0x41000000
	v_mov_b32_e32 v240, 0
	v_mov_b32_e32 v241, 0
	v_mov_b32_e32 v238, 0
	v_mov_b32_e32 v239, 0
	v_mov_b32_e32 v55, s1
	s_waitcnt lgkmcnt(0)
	ds_read_b32 v14, v55
	ds_read_b32 v15, v55 offset:4
	ds_read_b32 v16, v55 offset:8
	ds_read_b32 v54, v55 offset:12
	v_add_u32_e32 v55, 16, v55
	s_waitcnt lgkmcnt(0)
; __device__ __forceinline__ float ex2(float x) { return __builtin_amdgcn_exp2f(x); }
; __device__ __forceinline__ bf16x8 pack_p(const float* p) { u32x4 w; w.x = cvt_pk_bf16(p[0], p[1]); w.y = cvt_pk_bf16(p[2], p[3]); w.z = cvt_pk_bf16(p[4], p[5]); w.w = cvt_pk_bf16(p[6], p[7]); return __builtin_bit_cast(bf16x8, w); }
; __device__ __forceinline__ void flash16_compute(bool domask, const bf16x8 (&kf)[4], const bf16x8 (&vf)[4], const bf16x8 (&q)[2], int x0, unsigned span, float& m, float& l, f32x4v (&O)[4]) {
;     f32x4v s0 = {0.f, 0.f, 0.f, 0.f}, s1 = {0.f, 0.f, 0.f, 0.f};
;     __builtin_amdgcn_s_setprio(1);
;     s0 = mfma16(kf[0], q[0], s0); s1 = mfma16(kf[2], q[0], s1);
;     s0 = mfma16(kf[1], q[1], s0); s1 = mfma16(kf[3], q[1], s1);
;     __builtin_amdgcn_s_setprio(0);
;     float sc[8] = {s0[0], s0[1], s0[2], s0[3], s1[0], s1[1], s1[2], s1[3]};
;     if (domask) {
; #pragma unroll
;         for (int j = 0; j < 8; ++j) sc[j] = ((unsigned)(x0 + j) <= span) ? sc[j] : -1e30f;
;     }
;     float mx = fmaxf(fmaxf(fmaxf(sc[0], sc[1]), fmaxf(sc[2], sc[3])), fmaxf(fmaxf(sc[4], sc[5]), fmaxf(sc[6], sc[7])));
;     mx = xq_max(mx);
;     const bool upd = mx > m + SM_THR;
;     if (__ballot(upd) != 0ull) {
;         const float mn = upd ? mx : m, alpha = ex2(m - mn); l *= alpha;
; #pragma unroll
;         for (int dt = 0; dt < 4; ++dt) O[dt] = O[dt] * alpha;
;         m = mn;
;     }
;     const float msub = (m < -1e29f) ? 0.f : m;
;     float p[8], ps = 0.f;
; #pragma unroll
;     for (int j = 0; j < 8; ++j) { p[j] = ex2(sc[j] - msub); ps += p[j]; }
;     l += ps;
;     const bf16x8 pb = pack_p(p);
;     __builtin_amdgcn_s_setprio(1);
; #pragma unroll
;     for (int dt = 0; dt < 4; ++dt) O[dt] = mfma16(vf[dt], pb, O[dt]);
;     __builtin_amdgcn_s_setprio(0);
; }
; __device__ __forceinline__ void flash16_run(const bf16x8* kb, const bf16x8* vb, const bf16x8 (&qa)[2], const bf16x8 (&qb)[2], int nsteps, const LAS unsigned* list, int tq, int t0, int qi4, int fq, ...
;     ...
;     F16_LOAD(0, kA, vA, eA); F16_LOAD(1, kB, vB, eB);
; #pragma unroll 1
;     for (int s = 0; s < nsteps; s += 3) {
;         F16_LOAD(s + 2, kC, vC, eC); F16_COMP(kA, vA, eA); if (s + 1 >= nsteps) break;
;         F16_LOAD(s + 3, kA, vA, eA); F16_COMP(kB, vB, eB); if (s + 2 >= nsteps) break;
;         F16_LOAD(s + 4, kB, vB, eB); F16_COMP(kC, vC, eC);
	v_readfirstlane_b32 s16, v14
	v_readfirstlane_b32 s17, v15
	v_readfirstlane_b32 s19, v16
	s_and_b32 s6, s16, 0x7fff
	s_lshl_b32 s6, s6, 12
	v_lshl_add_u64 v[56:57], v[230:231], 0, s[6:7]
	v_lshl_add_u64 v[58:59], v[234:235], 0, s[6:7]
	global_load_dwordx4 v[114:117], v[56:57], off
	global_load_dwordx4 v[118:121], v[56:57], off offset:1024
	global_load_dwordx4 v[122:125], v[56:57], off offset:2048
	global_load_dwordx4 v[126:129], v[56:57], off offset:3072
	global_load_dwordx4 v[130:133], v[58:59], off
	global_load_dwordx4 v[134:137], v[58:59], off offset:1024
	global_load_dwordx4 v[138:141], v[58:59], off offset:2048
	global_load_dwordx4 v[142:145], v[58:59], off offset:3072
	s_and_b32 s6, s17, 0x7fff
	s_lshl_b32 s6, s6, 12
	v_lshl_add_u64 v[56:57], v[230:231], 0, s[6:7]
	v_lshl_add_u64 v[58:59], v[234:235], 0, s[6:7]
	global_load_dwordx4 v[146:149], v[56:57], off
	global_load_dwordx4 v[150:153], v[56:57], off offset:1024
	global_load_dwordx4 v[154:157], v[56:57], off offset:2048
	global_load_dwordx4 v[158:161], v[56:57], off offset:3072
	global_load_dwordx4 v[162:165], v[58:59], off
	global_load_dwordx4 v[166:169], v[58:59], off offset:1024
	global_load_dwordx4 v[170:173], v[58:59], off offset:2048
	global_load_dwordx4 v[174:177], v[58:59], off offset:3072
	s_and_b32 s6, s19, 0x7fff
	s_lshl_b32 s6, s6, 12
	v_lshl_add_u64 v[56:57], v[230:231], 0, s[6:7]
	v_lshl_add_u64 v[58:59], v[234:235], 0, s[6:7]
	global_load_dwordx4 v[178:181], v[56:57], off
	global_load_dwordx4 v[182:185], v[56:57], off offset:1024
	global_load_dwordx4 v[186:189], v[56:57], off offset:2048
	global_load_dwordx4 v[190:193], v[56:57], off offset:3072
	global_load_dwordx4 v[194:197], v[58:59], off
	global_load_dwordx4 v[198:201], v[58:59], off offset:1024
	global_load_dwordx4 v[202:205], v[58:59], off offset:2048
	global_load_dwordx4 v[206:209], v[58:59], off offset:3072
	s_mov_b32 s2, 0
.Lsel_step_A:
	s_waitcnt lgkmcnt(0)
	v_readfirstlane_b32 s4, v54
	ds_read_b32 v54, v55
	v_add_u32_e32 v55, 4, v55
	s_and_b32 s6, s4, 0x7fff
	s_lshl_b32 s6, s6, 12
	v_lshl_add_u64 v[56:57], v[230:231], 0, s[6:7]
	v_lshl_add_u64 v[58:59], v[234:235], 0, s[6:7]
	global_load_dwordx4 v[62:65], v[56:57], off
	global_load_dwordx4 v[66:69], v[56:57], off offset:1024
	global_load_dwordx4 v[70:73], v[56:57], off offset:2048
	global_load_dwordx4 v[74:77], v[56:57], off offset:3072
	global_load_dwordx4 v[78:81], v[58:59], off
	global_load_dwordx4 v[82:85], v[58:59], off offset:1024
	global_load_dwordx4 v[86:89], v[58:59], off offset:2048
	global_load_dwordx4 v[90:93], v[58:59], off offset:3072
	s_bfe_u32 s12, s16, 0x40010
	s_bfe_u32 s13, s16, 0x40014
	s_waitcnt vmcnt(24)
	s_cmp_eq_u32 s12, 0
	s_cbranch_scc1 .Lsel_skip_Aa
	v_and_b32_e32 v14, s12, v225
	v_cmp_eq_u32_e32 vcc, 0, v14
	s_bitcmp0_b32 s16, 15
	s_cbranch_scc1 .Lsel_slow_Aa
	v_cndmask_b32_e32 v10, v240, v249, vcc
	v_mov_b32_e32 v11, v10
	v_mov_b32_e32 v12, v10
	v_mov_b32_e32 v13, v10
	s_nop 1
	v_mfma_f32_16x16x32_bf16 v[2:5], v[114:117], v[102:105], v[10:13]
	v_mfma_f32_16x16x32_bf16 v[6:9], v[122:125], v[102:105], v[10:13]
.Lsel_qk2_Aa:
	v_mfma_f32_16x16x32_bf16 v[2:5], v[118:121], v[98:101], v[2:5]
	v_mfma_f32_16x16x32_bf16 v[6:9], v[126:129], v[98:101], v[6:9]
	s_nop 6
	v_max3_f32 v14, v2, v3, v4
	v_max3_f32 v16, v5, v6, v7
	v_max_f32_e32 v17, v8, v9
	v_max3_f32 v14, v14, v16, v17
	v_mov_b32_e32 v16, v14
	s_nop 1
	v_permlane16_swap_b32_e32 v14, v16
	v_max_f32_e32 v14, v14, v16
	v_mov_b32_e32 v16, v14
	s_nop 1
	v_permlane32_swap_b32_e32 v14, v16
	v_max_f32_e32 v14, v14, v16
	v_cmp_gt_f32_e32 vcc, v14, v94
	s_cbranch_vccnz .Lsel_upd_Aa
.Lsel_noupd_Aa:
	v_exp_f32_e32 v2, v2
	v_exp_f32_e32 v3, v3
	v_exp_f32_e32 v4, v4
	v_exp_f32_e32 v5, v5
	v_add_f32_e32 v14, v2, v3
	v_exp_f32_e32 v6, v6
	v_cvt_pk_bf16_f32 v50, v2, v3
	v_add_f32_e32 v14, v14, v4
	v_exp_f32_e32 v7, v7
	v_add_f32_e32 v14, v14, v5
	v_exp_f32_e32 v8, v8
	v_cvt_pk_bf16_f32 v51, v4, v5
	v_add_f32_e32 v14, v14, v6
	v_exp_f32_e32 v9, v9
	v_add_f32_e32 v14, v14, v7
	v_cvt_pk_bf16_f32 v52, v6, v7
	v_add_f32_e32 v14, v14, v8
	v_cvt_pk_bf16_f32 v53, v8, v9
	v_add_f32_e32 v14, v14, v9
	v_add_f32_e32 v238, v238, v14
	v_mfma_f32_16x16x32_bf16 v[34:37], v[130:133], v[50:53], v[34:37]
	v_mfma_f32_16x16x32_bf16 v[38:41], v[134:137], v[50:53], v[38:41]
	v_mfma_f32_16x16x32_bf16 v[42:45], v[138:141], v[50:53], v[42:45]
	v_mfma_f32_16x16x32_bf16 v[46:49], v[142:145], v[50:53], v[46:49]
.Lsel_skip_Aa:
	s_cmp_eq_u32 s13, 0
	s_cbranch_scc1 .Lsel_skip_Ab
	v_and_b32_e32 v14, s13, v225
	v_cmp_eq_u32_e32 vcc, 0, v14
	s_bitcmp0_b32 s16, 15
	s_cbranch_scc1 .Lsel_slow_Ab
	v_cndmask_b32_e32 v10, v241, v249, vcc
	v_mov_b32_e32 v11, v10
	v_mov_b32_e32 v12, v10
	v_mov_b32_e32 v13, v10
	s_nop 1
	v_mfma_f32_16x16x32_bf16 v[2:5], v[114:117], v[110:113], v[10:13]
	v_mfma_f32_16x16x32_bf16 v[6:9], v[122:125], v[110:113], v[10:13]
.Lsel_qk2_Ab:
	v_mfma_f32_16x16x32_bf16 v[2:5], v[118:121], v[106:109], v[2:5]
	v_mfma_f32_16x16x32_bf16 v[6:9], v[126:129], v[106:109], v[6:9]
	s_nop 6
	v_max3_f32 v14, v2, v3, v4
	v_max3_f32 v16, v5, v6, v7
	v_max_f32_e32 v17, v8, v9
	v_max3_f32 v14, v14, v16, v17
	v_mov_b32_e32 v16, v14
	s_nop 1
	v_permlane16_swap_b32_e32 v14, v16
	v_max_f32_e32 v14, v14, v16
	v_mov_b32_e32 v16, v14
	s_nop 1
	v_permlane32_swap_b32_e32 v14, v16
	v_max_f32_e32 v14, v14, v16
	v_cmp_gt_f32_e32 vcc, v14, v95
	s_cbranch_vccnz .Lsel_upd_Ab
.Lsel_noupd_Ab:
	v_exp_f32_e32 v2, v2
	v_exp_f32_e32 v3, v3
	v_exp_f32_e32 v4, v4
	v_exp_f32_e32 v5, v5
	v_add_f32_e32 v14, v2, v3
	v_exp_f32_e32 v6, v6
	v_cvt_pk_bf16_f32 v50, v2, v3
	v_add_f32_e32 v14, v14, v4
	v_exp_f32_e32 v7, v7
	v_add_f32_e32 v14, v14, v5
	v_exp_f32_e32 v8, v8
	v_cvt_pk_bf16_f32 v51, v4, v5
	v_add_f32_e32 v14, v14, v6
	v_exp_f32_e32 v9, v9
	v_add_f32_e32 v14, v14, v7
	v_cvt_pk_bf16_f32 v52, v6, v7
	v_add_f32_e32 v14, v14, v8
	v_cvt_pk_bf16_f32 v53, v8, v9
	v_add_f32_e32 v14, v14, v9
	v_add_f32_e32 v239, v239, v14
	v_mfma_f32_16x16x32_bf16 v[18:21], v[130:133], v[50:53], v[18:21]
	v_mfma_f32_16x16x32_bf16 v[22:25], v[134:137], v[50:53], v[22:25]
	v_mfma_f32_16x16x32_bf16 v[26:29], v[138:141], v[50:53], v[26:29]
	v_mfma_f32_16x16x32_bf16 v[30:33], v[142:145], v[50:53], v[30:33]

; __device__ __forceinline__ float ex2(float x) { return __builtin_amdgcn_exp2f(x); }
; __device__ __forceinline__ bf16x8 pack_p(const float* p) { u32x4 w; w.x = cvt_pk_bf16(p[0], p[1]); w.y = cvt_pk_bf16(p[2], p[3]); w.z = cvt_pk_bf16(p[4], p[5]); w.w = cvt_pk_bf16(p[6], p[7]); return __builtin_bit_cast(bf16x8, w); }
; __device__ __forceinline__ void flash16_compute(bool domask, const bf16x8 (&kf)[4], const bf16x8 (&vf)[4], const bf16x8 (&q)[2], int x0, unsigned span, float& m, float& l, f32x4v (&O)[4]) {
;     f32x4v s0 = {0.f, 0.f, 0.f, 0.f}, s1 = {0.f, 0.f, 0.f, 0.f};
;     __builtin_amdgcn_s_setprio(1);
;     s0 = mfma16(kf[0], q[0], s0); s1 = mfma16(kf[2], q[0], s1);
;     s0 = mfma16(kf[1], q[1], s0); s1 = mfma16(kf[3], q[1], s1);
;     __builtin_amdgcn_s_setprio(0);
;     float sc[8] = {s0[0], s0[1], s0[2], s0[3], s1[0], s1[1], s1[2], s1[3]};
;     if (domask) {
; #pragma unroll
;         for (int j = 0; j < 8; ++j) sc[j] = ((unsigned)(x0 + j) <= span) ? sc[j] : -1e30f;
;     }
;     float mx = fmaxf(fmaxf(fmaxf(sc[0], sc[1]), fmaxf(sc[2], sc[3])), fmaxf(fmaxf(sc[4], sc[5]), fmaxf(sc[6], sc[7])));
;     mx = xq_max(mx);
;     const bool upd = mx > m + SM_THR;
;     if (__ballot(upd) != 0ull) {
;         const float mn = upd ? mx : m, alpha = ex2(m - mn); l *= alpha;
; #pragma unroll
;         for (int dt = 0; dt < 4; ++dt) O[dt] = O[dt] * alpha;
;         m = mn;
;     }
;     const float msub = (m < -1e29f) ? 0.f : m;
;     float p[8], ps = 0.f;
; #pragma unroll
;     for (int j = 0; j < 8; ++j) { p[j] = ex2(sc[j] - msub); ps += p[j]; }
;     l += ps;
;     const bf16x8 pb = pack_p(p);
;     __builtin_amdgcn_s_setprio(1);
; #pragma unroll
;     for (int dt = 0; dt < 4; ++dt) O[dt] = mfma16(vf[dt], pb, O[dt]);
;     __builtin_amdgcn_s_setprio(0);
; }
; __device__ __forceinline__ void flash16_run(const bf16x8* kb, const bf16x8* vb, const bf16x8 (&qa)[2], const bf16x8 (&qb)[2], int nsteps, const LAS unsigned* list, int tq, int t0, int qi4, int fq, ...
;     ...
;     F16_LOAD(0, kA, vA, eA); F16_LOAD(1, kB, vB, eB);
; #pragma unroll 1
;     for (int s = 0; s < nsteps; s += 3) {
;         F16_LOAD(s + 2, kC, vC, eC); F16_COMP(kA, vA, eA); if (s + 1 >= nsteps) break;
;         F16_LOAD(s + 3, kA, vA, eA); F16_COMP(kB, vB, eB); if (s + 2 >= nsteps) break;
;         F16_LOAD(s + 4, kB, vB, eB); F16_COMP(kC, vC, eC);
.Lsel_step_B:
	s_waitcnt lgkmcnt(0)
	v_readfirstlane_b32 s16, v54
	ds_read_b32 v54, v55
	v_add_u32_e32 v55, 4, v55
	s_and_b32 s6, s16, 0x7fff
	s_lshl_b32 s6, s6, 12
	v_lshl_add_u64 v[56:57], v[230:231], 0, s[6:7]
	v_lshl_add_u64 v[58:59], v[234:235], 0, s[6:7]
	global_load_dwordx4 v[114:117], v[56:57], off
	global_load_dwordx4 v[118:121], v[56:57], off offset:1024
	global_load_dwordx4 v[122:125], v[56:57], off offset:2048
	global_load_dwordx4 v[126:129], v[56:57], off offset:3072
	global_load_dwordx4 v[130:133], v[58:59], off
	global_load_dwordx4 v[134:137], v[58:59], off offset:1024
	global_load_dwordx4 v[138:141], v[58:59], off offset:2048
	global_load_dwordx4 v[142:145], v[58:59], off offset:3072
	s_bfe_u32 s12, s17, 0x40010
	s_bfe_u32 s13, s17, 0x40014
	s_waitcnt vmcnt(24)
	s_cmp_eq_u32 s12, 0
	s_cbranch_scc1 .Lsel_skip_Ba
	v_and_b32_e32 v14, s12, v225
	v_cmp_eq_u32_e32 vcc, 0, v14
	s_bitcmp0_b32 s17, 15
	s_cbranch_scc1 .Lsel_slow_Ba
	v_cndmask_b32_e32 v10, v240, v249, vcc
	v_mov_b32_e32 v11, v10
	v_mov_b32_e32 v12, v10
	v_mov_b32_e32 v13, v10
	s_nop 1
	v_mfma_f32_16x16x32_bf16 v[2:5], v[146:149], v[102:105], v[10:13]
	v_mfma_f32_16x16x32_bf16 v[6:9], v[154:157], v[102:105], v[10:13]
.Lsel_qk2_Ba:
	v_mfma_f32_16x16x32_bf16 v[2:5], v[150:153], v[98:101], v[2:5]
	v_mfma_f32_16x16x32_bf16 v[6:9], v[158:161], v[98:101], v[6:9]
	s_nop 6
	v_max3_f32 v14, v2, v3, v4
	v_max3_f32 v16, v5, v6, v7
	v_max_f32_e32 v17, v8, v9
	v_max3_f32 v14, v14, v16, v17
	v_mov_b32_e32 v16, v14
	s_nop 1
	v_permlane16_swap_b32_e32 v14, v16
	v_max_f32_e32 v14, v14, v16
	v_mov_b32_e32 v16, v14
	s_nop 1
	v_permlane32_swap_b32_e32 v14, v16
	v_max_f32_e32 v14, v14, v16
	v_cmp_gt_f32_e32 vcc, v14, v94
	s_cbranch_vccnz .Lsel_upd_Ba
.Lsel_noupd_Ba:
	v_exp_f32_e32 v2, v2
	v_exp_f32_e32 v3, v3
	v_exp_f32_e32 v4, v4
	v_exp_f32_e32 v5, v5
	v_add_f32_e32 v14, v2, v3
	v_exp_f32_e32 v6, v6
	v_cvt_pk_bf16_f32 v50, v2, v3
	v_add_f32_e32 v14, v14, v4
	v_exp_f32_e32 v7, v7
	v_add_f32_e32 v14, v14, v5
	v_exp_f32_e32 v8, v8
	v_cvt_pk_bf16_f32 v51, v4, v5
	v_add_f32_e32 v14, v14, v6
	v_exp_f32_e32 v9, v9
	v_add_f32_e32 v14, v14, v7
	v_cvt_pk_bf16_f32 v52, v6, v7
	v_add_f32_e32 v14, v14, v8
	v_cvt_pk_bf16_f32 v53, v8, v9
	v_add_f32_e32 v14, v14, v9
	v_add_f32_e32 v238, v238, v14
	v_mfma_f32_16x16x32_bf16 v[34:37], v[162:165], v[50:53], v[34:37]
	v_mfma_f32_16x16x32_bf16 v[38:41], v[166:169], v[50:53], v[38:41]
	v_mfma_f32_16x16x32_bf16 v[42:45], v[170:173], v[50:53], v[42:45]
	v_mfma_f32_16x16x32_bf16 v[46:49], v[174:177], v[50:53], v[46:49]
.Lsel_skip_Ba:
	s_cmp_eq_u32 s13, 0
	s_cbranch_scc1 .Lsel_skip_Bb
	v_and_b32_e32 v14, s13, v225
	v_cmp_eq_u32_e32 vcc, 0, v14
	s_bitcmp0_b32 s17, 15
	s_cbranch_scc1 .Lsel_slow_Bb
	v_cndmask_b32_e32 v10, v241, v249, vcc
	v_mov_b32_e32 v11, v10
	v_mov_b32_e32 v12, v10
	v_mov_b32_e32 v13, v10
	s_nop 1
	v_mfma_f32_16x16x32_bf16 v[2:5], v[146:149], v[110:113], v[10:13]
	v_mfma_f32_16x16x32_bf16 v[6:9], v[154:157], v[110:113], v[10:13]
.Lsel_qk2_Bb:
	v_mfma_f32_16x16x32_bf16 v[2:5], v[150:153], v[106:109], v[2:5]
	v_mfma_f32_16x16x32_bf16 v[6:9], v[158:161], v[106:109], v[6:9]
	s_nop 6
	v_max3_f32 v14, v2, v3, v4
	v_max3_f32 v16, v5, v6, v7
	v_max_f32_e32 v17, v8, v9
	v_max3_f32 v14, v14, v16, v17
	v_mov_b32_e32 v16, v14
	s_nop 1
	v_permlane16_swap_b32_e32 v14, v16
	v_max_f32_e32 v14, v14, v16
	v_mov_b32_e32 v16, v14
	s_nop 1
	v_permlane32_swap_b32_e32 v14, v16
	v_max_f32_e32 v14, v14, v16
	v_cmp_gt_f32_e32 vcc, v14, v95
	s_cbranch_vccnz .Lsel_upd_Bb
.Lsel_noupd_Bb:
	v_exp_f32_e32 v2, v2
	v_exp_f32_e32 v3, v3
	v_exp_f32_e32 v4, v4
	v_exp_f32_e32 v5, v5
	v_add_f32_e32 v14, v2, v3
	v_exp_f32_e32 v6, v6
	v_cvt_pk_bf16_f32 v50, v2, v3
	v_add_f32_e32 v14, v14, v4
	v_exp_f32_e32 v7, v7
	v_add_f32_e32 v14, v14, v5
	v_exp_f32_e32 v8, v8
	v_cvt_pk_bf16_f32 v51, v4, v5
	v_add_f32_e32 v14, v14, v6
	v_exp_f32_e32 v9, v9
	v_add_f32_e32 v14, v14, v7
	v_cvt_pk_bf16_f32 v52, v6, v7
	v_add_f32_e32 v14, v14, v8
	v_cvt_pk_bf16_f32 v53, v8, v9
	v_add_f32_e32 v14, v14, v9
	v_add_f32_e32 v239, v239, v14
	v_mfma_f32_16x16x32_bf16 v[18:21], v[162:165], v[50:53], v[18:21]
	v_mfma_f32_16x16x32_bf16 v[22:25], v[166:169], v[50:53], v[22:25]
	v_mfma_f32_16x16x32_bf16 v[26:29], v[170:173], v[50:53], v[26:29]
	v_mfma_f32_16x16x32_bf16 v[30:33], v[174:177], v[50:53], v[30:33]

; __device__ __forceinline__ float ex2(float x) { return __builtin_amdgcn_exp2f(x); }
; __device__ __forceinline__ bf16x8 pack_p(const float* p) { u32x4 w; w.x = cvt_pk_bf16(p[0], p[1]); w.y = cvt_pk_bf16(p[2], p[3]); w.z = cvt_pk_bf16(p[4], p[5]); w.w = cvt_pk_bf16(p[6], p[7]); return __builtin_bit_cast(bf16x8, w); }
; __device__ __forceinline__ void flash16_compute(bool domask, const bf16x8 (&kf)[4], const bf16x8 (&vf)[4], const bf16x8 (&q)[2], int x0, unsigned span, float& m, float& l, f32x4v (&O)[4]) {
;     f32x4v s0 = {0.f, 0.f, 0.f, 0.f}, s1 = {0.f, 0.f, 0.f, 0.f};
;     __builtin_amdgcn_s_setprio(1);
;     s0 = mfma16(kf[0], q[0], s0); s1 = mfma16(kf[2], q[0], s1);
;     s0 = mfma16(kf[1], q[1], s0); s1 = mfma16(kf[3], q[1], s1);
;     __builtin_amdgcn_s_setprio(0);
;     float sc[8] = {s0[0], s0[1], s0[2], s0[3], s1[0], s1[1], s1[2], s1[3]};
;     if (domask) {
; #pragma unroll
;         for (int j = 0; j < 8; ++j) sc[j] = ((unsigned)(x0 + j) <= span) ? sc[j] : -1e30f;
;     }
;     float mx = fmaxf(fmaxf(fmaxf(sc[0], sc[1]), fmaxf(sc[2], sc[3])), fmaxf(fmaxf(sc[4], sc[5]), fmaxf(sc[6], sc[7])));
;     mx = xq_max(mx);
;     const bool upd = mx > m + SM_THR;
;     if (__ballot(upd) != 0ull) {
;         const float mn = upd ? mx : m, alpha = ex2(m - mn); l *= alpha;
; #pragma unroll
;         for (int dt = 0; dt < 4; ++dt) O[dt] = O[dt] * alpha;
;         m = mn;
;     }
;     const float msub = (m < -1e29f) ? 0.f : m;
;     float p[8], ps = 0.f;
; #pragma unroll
;     for (int j = 0; j < 8; ++j) { p[j] = ex2(sc[j] - msub); ps += p[j]; }
;     l += ps;
;     const bf16x8 pb = pack_p(p);
;     __builtin_amdgcn_s_setprio(1);
; #pragma unroll
;     for (int dt = 0; dt < 4; ++dt) O[dt] = mfma16(vf[dt], pb, O[dt]);
;     __builtin_amdgcn_s_setprio(0);
; }
; __device__ __forceinline__ void flash16_run(const bf16x8* kb, const bf16x8* vb, const bf16x8 (&qa)[2], const bf16x8 (&qb)[2], int nsteps, const LAS unsigned* list, int tq, int t0, int qi4, int fq, ...
;     ...
;     F16_LOAD(0, kA, vA, eA); F16_LOAD(1, kB, vB, eB);
; #pragma unroll 1
;     for (int s = 0; s < nsteps; s += 3) {
;         F16_LOAD(s + 2, kC, vC, eC); F16_COMP(kA, vA, eA); if (s + 1 >= nsteps) break;
;         F16_LOAD(s + 3, kA, vA, eA); F16_COMP(kB, vB, eB); if (s + 2 >= nsteps) break;
;         F16_LOAD(s + 4, kB, vB, eB); F16_COMP(kC, vC, eC);
.Lsel_step_C:
	s_waitcnt lgkmcnt(0)
	v_readfirstlane_b32 s17, v54
	ds_read_b32 v54, v55
	v_add_u32_e32 v55, 4, v55
	s_and_b32 s6, s17, 0x7fff
	s_lshl_b32 s6, s6, 12
	v_lshl_add_u64 v[56:57], v[230:231], 0, s[6:7]
	v_lshl_add_u64 v[58:59], v[234:235], 0, s[6:7]
	global_load_dwordx4 v[146:149], v[56:57], off
	global_load_dwordx4 v[150:153], v[56:57], off offset:1024
	global_load_dwordx4 v[154:157], v[56:57], off offset:2048
	global_load_dwordx4 v[158:161], v[56:57], off offset:3072
	global_load_dwordx4 v[162:165], v[58:59], off
	global_load_dwordx4 v[166:169], v[58:59], off offset:1024
	global_load_dwordx4 v[170:173], v[58:59], off offset:2048
	global_load_dwordx4 v[174:177], v[58:59], off offset:3072
	s_bfe_u32 s12, s19, 0x40010
	s_bfe_u32 s13, s19, 0x40014
	s_waitcnt vmcnt(24)
	s_cmp_eq_u32 s12, 0
	s_cbranch_scc1 .Lsel_skip_Ca
	v_and_b32_e32 v14, s12, v225
	v_cmp_eq_u32_e32 vcc, 0, v14
	s_bitcmp0_b32 s19, 15
	s_cbranch_scc1 .Lsel_slow_Ca
	v_cndmask_b32_e32 v10, v240, v249, vcc
	v_mov_b32_e32 v11, v10
	v_mov_b32_e32 v12, v10
	v_mov_b32_e32 v13, v10
	s_nop 1
	v_mfma_f32_16x16x32_bf16 v[2:5], v[178:181], v[102:105], v[10:13]
	v_mfma_f32_16x16x32_bf16 v[6:9], v[186:189], v[102:105], v[10:13]
.Lsel_qk2_Ca:
	v_mfma_f32_16x16x32_bf16 v[2:5], v[182:185], v[98:101], v[2:5]
	v_mfma_f32_16x16x32_bf16 v[6:9], v[190:193], v[98:101], v[6:9]
	s_nop 6
	v_max3_f32 v14, v2, v3, v4
	v_max3_f32 v16, v5, v6, v7
	v_max_f32_e32 v17, v8, v9
	v_max3_f32 v14, v14, v16, v17
	v_mov_b32_e32 v16, v14
	s_nop 1
	v_permlane16_swap_b32_e32 v14, v16
	v_max_f32_e32 v14, v14, v16
	v_mov_b32_e32 v16, v14
	s_nop 1
	v_permlane32_swap_b32_e32 v14, v16
	v_max_f32_e32 v14, v14, v16
	v_cmp_gt_f32_e32 vcc, v14, v94
	s_cbranch_vccnz .Lsel_upd_Ca
.Lsel_noupd_Ca:
	v_exp_f32_e32 v2, v2
	v_exp_f32_e32 v3, v3
	v_exp_f32_e32 v4, v4
	v_exp_f32_e32 v5, v5
	v_add_f32_e32 v14, v2, v3
	v_exp_f32_e32 v6, v6
	v_cvt_pk_bf16_f32 v50, v2, v3
	v_add_f32_e32 v14, v14, v4
	v_exp_f32_e32 v7, v7
	v_add_f32_e32 v14, v14, v5
	v_exp_f32_e32 v8, v8
	v_cvt_pk_bf16_f32 v51, v4, v5
	v_add_f32_e32 v14, v14, v6
	v_exp_f32_e32 v9, v9
	v_add_f32_e32 v14, v14, v7
	v_cvt_pk_bf16_f32 v52, v6, v7
	v_add_f32_e32 v14, v14, v8
	v_cvt_pk_bf16_f32 v53, v8, v9
	v_add_f32_e32 v14, v14, v9
	v_add_f32_e32 v238, v238, v14
	v_mfma_f32_16x16x32_bf16 v[34:37], v[194:197], v[50:53], v[34:37]
	v_mfma_f32_16x16x32_bf16 v[38:41], v[198:201], v[50:53], v[38:41]
	v_mfma_f32_16x16x32_bf16 v[42:45], v[202:205], v[50:53], v[42:45]
	v_mfma_f32_16x16x32_bf16 v[46:49], v[206:209], v[50:53], v[46:49]
.Lsel_skip_Ca:
	s_cmp_eq_u32 s13, 0
	s_cbranch_scc1 .Lsel_skip_Cb
	v_and_b32_e32 v14, s13, v225
	v_cmp_eq_u32_e32 vcc, 0, v14
	s_bitcmp0_b32 s19, 15
	s_cbranch_scc1 .Lsel_slow_Cb
	v_cndmask_b32_e32 v10, v241, v249, vcc
	v_mov_b32_e32 v11, v10
	v_mov_b32_e32 v12, v10
	v_mov_b32_e32 v13, v10
	s_nop 1
	v_mfma_f32_16x16x32_bf16 v[2:5], v[178:181], v[110:113], v[10:13]
	v_mfma_f32_16x16x32_bf16 v[6:9], v[186:189], v[110:113], v[10:13]
.Lsel_qk2_Cb:
	v_mfma_f32_16x16x32_bf16 v[2:5], v[182:185], v[106:109], v[2:5]
	v_mfma_f32_16x16x32_bf16 v[6:9], v[190:193], v[106:109], v[6:9]
	s_nop 6
	v_max3_f32 v14, v2, v3, v4
	v_max3_f32 v16, v5, v6, v7
	v_max_f32_e32 v17, v8, v9
	v_max3_f32 v14, v14, v16, v17
	v_mov_b32_e32 v16, v14
	s_nop 1
	v_permlane16_swap_b32_e32 v14, v16
	v_max_f32_e32 v14, v14, v16
	v_mov_b32_e32 v16, v14
	s_nop 1
	v_permlane32_swap_b32_e32 v14, v16
	v_max_f32_e32 v14, v14, v16
	v_cmp_gt_f32_e32 vcc, v14, v95
	s_cbranch_vccnz .Lsel_upd_Cb
.Lsel_noupd_Cb:
	v_exp_f32_e32 v2, v2
	v_exp_f32_e32 v3, v3
	v_exp_f32_e32 v4, v4
	v_exp_f32_e32 v5, v5
	v_add_f32_e32 v14, v2, v3
	v_exp_f32_e32 v6, v6
	v_cvt_pk_bf16_f32 v50, v2, v3
	v_add_f32_e32 v14, v14, v4
	v_exp_f32_e32 v7, v7
	v_add_f32_e32 v14, v14, v5
	v_exp_f32_e32 v8, v8
	v_cvt_pk_bf16_f32 v51, v4, v5
	v_add_f32_e32 v14, v14, v6
	v_exp_f32_e32 v9, v9
	v_add_f32_e32 v14, v14, v7
	v_cvt_pk_bf16_f32 v52, v6, v7
	v_add_f32_e32 v14, v14, v8
	v_cvt_pk_bf16_f32 v53, v8, v9
	v_add_f32_e32 v14, v14, v9
	v_add_f32_e32 v239, v239, v14
	v_mfma_f32_16x16x32_bf16 v[18:21], v[194:197], v[50:53], v[18:21]
	v_mfma_f32_16x16x32_bf16 v[22:25], v[198:201], v[50:53], v[22:25]
	v_mfma_f32_16x16x32_bf16 v[26:29], v[202:205], v[50:53], v[26:29]
	v_mfma_f32_16x16x32_bf16 v[30:33], v[206:209], v[50:53], v[30:33]

; __device__ __forceinline__ float ex2(float x) { return __builtin_amdgcn_exp2f(x); }
; __device__ __forceinline__ bf16x8 pack_p(const float* p) { u32x4 w; w.x = cvt_pk_bf16(p[0], p[1]); w.y = cvt_pk_bf16(p[2], p[3]); w.z = cvt_pk_bf16(p[4], p[5]); w.w = cvt_pk_bf16(p[6], p[7]); return __builtin_bit_cast(bf16x8, w); }
; __device__ __forceinline__ void flash16_compute(bool domask, const bf16x8 (&kf)[4], const bf16x8 (&vf)[4], const bf16x8 (&q)[2], int x0, unsigned span, float& m, float& l, f32x4v (&O)[4]) {
;     f32x4v s0 = {0.f, 0.f, 0.f, 0.f}, s1 = {0.f, 0.f, 0.f, 0.f};
;     __builtin_amdgcn_s_setprio(1);
;     s0 = mfma16(kf[0], q[0], s0); s1 = mfma16(kf[2], q[0], s1);
;     s0 = mfma16(kf[1], q[1], s0); s1 = mfma16(kf[3], q[1], s1);
;     __builtin_amdgcn_s_setprio(0);
;     float sc[8] = {s0[0], s0[1], s0[2], s0[3], s1[0], s1[1], s1[2], s1[3]};
;     if (domask) {
; #pragma unroll
;         for (int j = 0; j < 8; ++j) sc[j] = ((unsigned)(x0 + j) <= span) ? sc[j] : -1e30f;
;     }
;     float mx = fmaxf(fmaxf(fmaxf(sc[0], sc[1]), fmaxf(sc[2], sc[3])), fmaxf(fmaxf(sc[4], sc[5]), fmaxf(sc[6], sc[7])));
;     mx = xq_max(mx);
;     const bool upd = mx > m + SM_THR;
;     if (__ballot(upd) != 0ull) {
;         const float mn = upd ? mx : m, alpha = ex2(m - mn); l *= alpha;
; #pragma unroll
;         for (int dt = 0; dt < 4; ++dt) O[dt] = O[dt] * alpha;
;         m = mn;
;     }
;     const float msub = (m < -1e29f) ? 0.f : m;
;     float p[8], ps = 0.f;
; #pragma unroll
;     for (int j = 0; j < 8; ++j) { p[j] = ex2(sc[j] - msub); ps += p[j]; }
;     l += ps;
;     const bf16x8 pb = pack_p(p);
;     __builtin_amdgcn_s_setprio(1);
; #pragma unroll
;     for (int dt = 0; dt < 4; ++dt) O[dt] = mfma16(vf[dt], pb, O[dt]);
;     __builtin_amdgcn_s_setprio(0);
; }
; __device__ __forceinline__ void flash16_run(const bf16x8* kb, const bf16x8* vb, const bf16x8 (&qa)[2], const bf16x8 (&qb)[2], int nsteps, const LAS unsigned* list, int tq, int t0, int qi4, int fq, ...
;     ...
;     F16_LOAD(0, kA, vA, eA); F16_LOAD(1, kB, vB, eB);
; #pragma unroll 1
;     for (int s = 0; s < nsteps; s += 3) {
;         F16_LOAD(s + 2, kC, vC, eC); F16_COMP(kA, vA, eA); if (s + 1 >= nsteps) break;
;         F16_LOAD(s + 3, kA, vA, eA); F16_COMP(kB, vB, eB); if (s + 2 >= nsteps) break;
;         F16_LOAD(s + 4, kB, vB, eB); F16_COMP(kC, vC, eC);
.Lsel_step_D:
	s_waitcnt lgkmcnt(0)
	v_readfirstlane_b32 s19, v54
	ds_read_b32 v54, v55
	v_add_u32_e32 v55, 4, v55
	s_and_b32 s6, s19, 0x7fff
	s_lshl_b32 s6, s6, 12
	v_lshl_add_u64 v[56:57], v[230:231], 0, s[6:7]
	v_lshl_add_u64 v[58:59], v[234:235], 0, s[6:7]
	global_load_dwordx4 v[178:181], v[56:57], off
	global_load_dwordx4 v[182:185], v[56:57], off offset:1024
	global_load_dwordx4 v[186:189], v[56:57], off offset:2048
	global_load_dwordx4 v[190:193], v[56:57], off offset:3072
	global_load_dwordx4 v[194:197], v[58:59], off
	global_load_dwordx4 v[198:201], v[58:59], off offset:1024
	global_load_dwordx4 v[202:205], v[58:59], off offset:2048
	global_load_dwordx4 v[206:209], v[58:59], off offset:3072
	s_bfe_u32 s12, s4, 0x40010
	s_bfe_u32 s13, s4, 0x40014
	s_waitcnt vmcnt(24)
	s_cmp_eq_u32 s12, 0
	s_cbranch_scc1 .Lsel_skip_Da
	v_and_b32_e32 v14, s12, v225
	v_cmp_eq_u32_e32 vcc, 0, v14
	s_bitcmp0_b32 s4, 15
	s_cbranch_scc1 .Lsel_slow_Da
	v_cndmask_b32_e32 v10, v240, v249, vcc
	v_mov_b32_e32 v11, v10
	v_mov_b32_e32 v12, v10
	v_mov_b32_e32 v13, v10
	s_nop 1
	v_mfma_f32_16x16x32_bf16 v[2:5], v[62:65], v[102:105], v[10:13]
	v_mfma_f32_16x16x32_bf16 v[6:9], v[70:73], v[102:105], v[10:13]
.Lsel_qk2_Da:
	v_mfma_f32_16x16x32_bf16 v[2:5], v[66:69], v[98:101], v[2:5]
	v_mfma_f32_16x16x32_bf16 v[6:9], v[74:77], v[98:101], v[6:9]
	s_nop 6
	v_max3_f32 v14, v2, v3, v4
	v_max3_f32 v16, v5, v6, v7
	v_max_f32_e32 v17, v8, v9
	v_max3_f32 v14, v14, v16, v17
	v_mov_b32_e32 v16, v14
	s_nop 1
	v_permlane16_swap_b32_e32 v14, v16
	v_max_f32_e32 v14, v14, v16
	v_mov_b32_e32 v16, v14
	s_nop 1
	v_permlane32_swap_b32_e32 v14, v16
	v_max_f32_e32 v14, v14, v16
	v_cmp_gt_f32_e32 vcc, v14, v94
	s_cbranch_vccnz .Lsel_upd_Da
.Lsel_noupd_Da:
	v_exp_f32_e32 v2, v2
	v_exp_f32_e32 v3, v3
	v_exp_f32_e32 v4, v4
	v_exp_f32_e32 v5, v5
	v_add_f32_e32 v14, v2, v3
	v_exp_f32_e32 v6, v6
	v_cvt_pk_bf16_f32 v50, v2, v3
	v_add_f32_e32 v14, v14, v4
	v_exp_f32_e32 v7, v7
	v_add_f32_e32 v14, v14, v5
	v_exp_f32_e32 v8, v8
	v_cvt_pk_bf16_f32 v51, v4, v5
	v_add_f32_e32 v14, v14, v6
	v_exp_f32_e32 v9, v9
	v_add_f32_e32 v14, v14, v7
	v_cvt_pk_bf16_f32 v52, v6, v7
	v_add_f32_e32 v14, v14, v8
	v_cvt_pk_bf16_f32 v53, v8, v9
	v_add_f32_e32 v14, v14, v9
	v_add_f32_e32 v238, v238, v14
	v_mfma_f32_16x16x32_bf16 v[34:37], v[78:81], v[50:53], v[34:37]
	v_mfma_f32_16x16x32_bf16 v[38:41], v[82:85], v[50:53], v[38:41]
	v_mfma_f32_16x16x32_bf16 v[42:45], v[86:89], v[50:53], v[42:45]
	v_mfma_f32_16x16x32_bf16 v[46:49], v[90:93], v[50:53], v[46:49]
.Lsel_skip_Da:
	s_cmp_eq_u32 s13, 0
	s_cbranch_scc1 .Lsel_skip_Db
	v_and_b32_e32 v14, s13, v225
	v_cmp_eq_u32_e32 vcc, 0, v14
	s_bitcmp0_b32 s4, 15
	s_cbranch_scc1 .Lsel_slow_Db
	v_cndmask_b32_e32 v10, v241, v249, vcc
	v_mov_b32_e32 v11, v10
	v_mov_b32_e32 v12, v10
	v_mov_b32_e32 v13, v10
	s_nop 1
	v_mfma_f32_16x16x32_bf16 v[2:5], v[62:65], v[110:113], v[10:13]
	v_mfma_f32_16x16x32_bf16 v[6:9], v[70:73], v[110:113], v[10:13]
.Lsel_qk2_Db:
	v_mfma_f32_16x16x32_bf16 v[2:5], v[66:69], v[106:109], v[2:5]
	v_mfma_f32_16x16x32_bf16 v[6:9], v[74:77], v[106:109], v[6:9]
	s_nop 6
	v_max3_f32 v14, v2, v3, v4
	v_max3_f32 v16, v5, v6, v7
	v_max_f32_e32 v17, v8, v9
	v_max3_f32 v14, v14, v16, v17
	v_mov_b32_e32 v16, v14
	s_nop 1
	v_permlane16_swap_b32_e32 v14, v16
	v_max_f32_e32 v14, v14, v16
	v_mov_b32_e32 v16, v14
	s_nop 1
	v_permlane32_swap_b32_e32 v14, v16
	v_max_f32_e32 v14, v14, v16
	v_cmp_gt_f32_e32 vcc, v14, v95
	s_cbranch_vccnz .Lsel_upd_Db
.Lsel_noupd_Db:
	v_exp_f32_e32 v2, v2
	v_exp_f32_e32 v3, v3
	v_exp_f32_e32 v4, v4
	v_exp_f32_e32 v5, v5
	v_add_f32_e32 v14, v2, v3
	v_exp_f32_e32 v6, v6
	v_cvt_pk_bf16_f32 v50, v2, v3
	v_add_f32_e32 v14, v14, v4
	v_exp_f32_e32 v7, v7
	v_add_f32_e32 v14, v14, v5
	v_exp_f32_e32 v8, v8
	v_cvt_pk_bf16_f32 v51, v4, v5
	v_add_f32_e32 v14, v14, v6
	v_exp_f32_e32 v9, v9
	v_add_f32_e32 v14, v14, v7
	v_cvt_pk_bf16_f32 v52, v6, v7
	v_add_f32_e32 v14, v14, v8
	v_cvt_pk_bf16_f32 v53, v8, v9
	v_add_f32_e32 v14, v14, v9
	v_add_f32_e32 v239, v239, v14
	v_mfma_f32_16x16x32_bf16 v[18:21], v[78:81], v[50:53], v[18:21]
	v_mfma_f32_16x16x32_bf16 v[22:25], v[82:85], v[50:53], v[22:25]
	v_mfma_f32_16x16x32_bf16 v[26:29], v[86:89], v[50:53], v[26:29]
	v_mfma_f32_16x16x32_bf16 v[30:33], v[90:93], v[50:53], v[30:33]

; __device__ __forceinline__ float ex2(float x) { return __builtin_amdgcn_exp2f(x); }
; __device__ __forceinline__ f32x4v mfma16(bf16x8 a, bf16x8 b, f32x4v c) { return __builtin_amdgcn_mfma_f32_16x16x32_bf16(a, b, c, 0, 0, 0); }
; __device__ __forceinline__ float xq_max(float v) { const auto r = __builtin_amdgcn_permlane16_swap(__float_as_uint(v), __float_as_uint(v), false, false); return xhalf_max(fmaxf(__uint_as_float(r[0]), __uint_as_float(r[1]))); }
; __device__ __forceinline__ void flash16_compute(bool domask, const bf16x8 (&kf)[4], const bf16x8 (&vf)[4], const bf16x8 (&q)[2], int x0, unsigned span, float& m, float& l, f32x4v (&O)[4]) {
;     f32x4v s0 = {0.f, 0.f, 0.f, 0.f}, s1 = {0.f, 0.f, 0.f, 0.f};
;     __builtin_amdgcn_s_setprio(1);
;     s0 = mfma16(kf[0], q[0], s0); s1 = mfma16(kf[2], q[0], s1);
;     s0 = mfma16(kf[1], q[1], s0); s1 = mfma16(kf[3], q[1], s1);
;     __builtin_amdgcn_s_setprio(0);
;     float sc[8] = {s0[0], s0[1], s0[2], s0[3], s1[0], s1[1], s1[2], s1[3]};
;     if (domask) {
; #pragma unroll
;         for (int j = 0; j < 8; ++j) sc[j] = ((unsigned)(x0 + j) <= span) ? sc[j] : -1e30f;
;     }
;     float mx = fmaxf(fmaxf(fmaxf(sc[0], sc[1]), fmaxf(sc[2], sc[3])), fmaxf(fmaxf(sc[4], sc[5]), fmaxf(sc[6], sc[7])));
;     mx = xq_max(mx);
;     const bool upd = mx > m + SM_THR;
;     if (__ballot(upd) != 0ull) {
;         const float mn = upd ? mx : m, alpha = ex2(m - mn); l *= alpha;
; #pragma unroll
;         for (int dt = 0; dt < 4; ++dt) O[dt] = O[dt] * alpha;
;         m = mn;
;     }
.Lsel_slow_Aa:
	s_and_b32 s10, s16, 0x7fff
	s_lshl_b32 s10, s10, 5
	v_subrev_u32_e32 v16, s10, v211
	s_nop 0
	v_cndmask_b32_e64 v16, v16, -1, vcc
	v_cmp_lt_i32_e32 vcc, -1, v16
	v_max_i32_e32 v17, 0, v16
	s_nop 0
	v_cndmask_b32_e32 v16, 64, v232, vcc
	v_cmp_le_u32_e32 vcc, v16, v17
	s_nop 1
	v_cndmask_b32_e32 v2, v249, v240, vcc
	v_or_b32_e32 v15, 1, v16
	v_cmp_le_u32_e32 vcc, v15, v17
	s_nop 1
	v_cndmask_b32_e32 v3, v249, v240, vcc
	v_or_b32_e32 v15, 2, v16
	v_cmp_le_u32_e32 vcc, v15, v17
	s_nop 1
	v_cndmask_b32_e32 v4, v249, v240, vcc
	v_or_b32_e32 v15, 3, v16
	v_cmp_le_u32_e32 vcc, v15, v17
	s_nop 1
	v_cndmask_b32_e32 v5, v249, v240, vcc
	v_or_b32_e32 v15, 4, v16
	v_cmp_le_u32_e32 vcc, v15, v17
	s_nop 1
	v_cndmask_b32_e32 v6, v249, v240, vcc
	v_or_b32_e32 v15, 5, v16
	v_cmp_le_u32_e32 vcc, v15, v17
	s_nop 1
	v_cndmask_b32_e32 v7, v249, v240, vcc
	v_or_b32_e32 v15, 6, v16
	v_cmp_le_u32_e32 vcc, v15, v17
	s_nop 1
	v_cndmask_b32_e32 v8, v249, v240, vcc
	v_or_b32_e32 v15, 7, v16
	v_cmp_le_u32_e32 vcc, v15, v17
	s_nop 1
	v_cndmask_b32_e32 v9, v249, v240, vcc
	s_nop 1
	v_mfma_f32_16x16x32_bf16 v[2:5], v[114:117], v[102:105], v[2:5]
	v_mfma_f32_16x16x32_bf16 v[6:9], v[122:125], v[102:105], v[6:9]
	s_branch .Lsel_qk2_Aa
.Lsel_upd_Aa:
	s_nop 1
	v_cndmask_b32_e32 v16, 0, v14, vcc
	v_sub_f32_e32 v17, v14, v240
	v_cndmask_b32_e32 v17, v236, v17, vcc
	v_sub_f32_e32 v15, v236, v17
	v_exp_f32_e32 v15, v15
	v_mov_b32_e32 v236, v17
	v_cndmask_b32_e64 v240, v240, -v17, vcc
	v_cndmask_b32_e32 v94, v94, v96, vcc
	v_mul_f32_e32 v238, v238, v15
	v_mul_f32_e32 v34, v34, v15
	v_mul_f32_e32 v35, v35, v15
	v_mul_f32_e32 v36, v36, v15
	v_mul_f32_e32 v37, v37, v15
	v_mul_f32_e32 v38, v38, v15
	v_mul_f32_e32 v39, v39, v15
	v_mul_f32_e32 v40, v40, v15
	v_mul_f32_e32 v41, v41, v15
	v_mul_f32_e32 v42, v42, v15
	v_mul_f32_e32 v43, v43, v15
	v_mul_f32_e32 v44, v44, v15
	v_mul_f32_e32 v45, v45, v15
	v_mul_f32_e32 v46, v46, v15
	v_mul_f32_e32 v47, v47, v15
	v_mul_f32_e32 v48, v48, v15
	v_mul_f32_e32 v49, v49, v15
	v_sub_f32_e32 v2, v2, v16
	v_sub_f32_e32 v3, v3, v16
	v_sub_f32_e32 v4, v4, v16
	v_sub_f32_e32 v5, v5, v16
	v_sub_f32_e32 v6, v6, v16
	v_sub_f32_e32 v7, v7, v16
	v_sub_f32_e32 v8, v8, v16
	v_sub_f32_e32 v9, v9, v16
	s_branch .Lsel_noupd_Aa
.Lsel_slow_Ab:
	s_and_b32 s10, s16, 0x7fff
	s_lshl_b32 s10, s10, 5
	v_subrev_u32_e32 v16, s10, v227
	s_nop 0
	v_cndmask_b32_e64 v16, v16, -1, vcc
	v_cmp_lt_i32_e32 vcc, -1, v16
	v_max_i32_e32 v17, 0, v16
	s_nop 0
	v_cndmask_b32_e32 v16, 64, v232, vcc
	v_cmp_le_u32_e32 vcc, v16, v17
	s_nop 1
	v_cndmask_b32_e32 v2, v249, v241, vcc
	v_or_b32_e32 v15, 1, v16
	v_cmp_le_u32_e32 vcc, v15, v17
	s_nop 1
	v_cndmask_b32_e32 v3, v249, v241, vcc
	v_or_b32_e32 v15, 2, v16
	v_cmp_le_u32_e32 vcc, v15, v17
	s_nop 1
	v_cndmask_b32_e32 v4, v249, v241, vcc
	v_or_b32_e32 v15, 3, v16
	v_cmp_le_u32_e32 vcc, v15, v17
	s_nop 1
	v_cndmask_b32_e32 v5, v249, v241, vcc
	v_or_b32_e32 v15, 4, v16
	v_cmp_le_u32_e32 vcc, v15, v17
	s_nop 1
	v_cndmask_b32_e32 v6, v249, v241, vcc
	v_or_b32_e32 v15, 5, v16
	v_cmp_le_u32_e32 vcc, v15, v17
	s_nop 1
	v_cndmask_b32_e32 v7, v249, v241, vcc
	v_or_b32_e32 v15, 6, v16
	v_cmp_le_u32_e32 vcc, v15, v17
	s_nop 1
	v_cndmask_b32_e32 v8, v249, v241, vcc
	v_or_b32_e32 v15, 7, v16
	v_cmp_le_u32_e32 vcc, v15, v17
	s_nop 1
	v_cndmask_b32_e32 v9, v249, v241, vcc
	s_nop 1
	v_mfma_f32_16x16x32_bf16 v[2:5], v[114:117], v[110:113], v[2:5]
	v_mfma_f32_16x16x32_bf16 v[6:9], v[122:125], v[110:113], v[6:9]
	s_branch .Lsel_qk2_Ab
.Lsel_upd_Ab:
	s_nop 1
	v_cndmask_b32_e32 v16, 0, v14, vcc
	v_sub_f32_e32 v17, v14, v241
	v_cndmask_b32_e32 v17, v237, v17, vcc
	v_sub_f32_e32 v15, v237, v17
	v_exp_f32_e32 v15, v15
	v_mov_b32_e32 v237, v17
	v_cndmask_b32_e64 v241, v241, -v17, vcc
	v_cndmask_b32_e32 v95, v95, v96, vcc
	v_mul_f32_e32 v239, v239, v15
	v_mul_f32_e32 v18, v18, v15
	v_mul_f32_e32 v19, v19, v15
	v_mul_f32_e32 v20, v20, v15
	v_mul_f32_e32 v21, v21, v15
	v_mul_f32_e32 v22, v22, v15
	v_mul_f32_e32 v23, v23, v15
	v_mul_f32_e32 v24, v24, v15
	v_mul_f32_e32 v25, v25, v15
	v_mul_f32_e32 v26, v26, v15
	v_mul_f32_e32 v27, v27, v15
	v_mul_f32_e32 v28, v28, v15
	v_mul_f32_e32 v29, v29, v15
	v_mul_f32_e32 v30, v30, v15
	v_mul_f32_e32 v31, v31, v15
	v_mul_f32_e32 v32, v32, v15
	v_mul_f32_e32 v33, v33, v15
	v_sub_f32_e32 v2, v2, v16
	v_sub_f32_e32 v3, v3, v16
	v_sub_f32_e32 v4, v4, v16
	v_sub_f32_e32 v5, v5, v16
	v_sub_f32_e32 v6, v6, v16
	v_sub_f32_e32 v7, v7, v16
	v_sub_f32_e32 v8, v8, v16
	v_sub_f32_e32 v9, v9, v16
	s_branch .Lsel_noupd_Ab
.Lsel_slow_Ba:
	s_and_b32 s10, s17, 0x7fff
	s_lshl_b32 s10, s10, 5
	v_subrev_u32_e32 v16, s10, v211
	s_nop 0
	v_cndmask_b32_e64 v16, v16, -1, vcc
	v_cmp_lt_i32_e32 vcc, -1, v16
	v_max_i32_e32 v17, 0, v16
	s_nop 0
	v_cndmask_b32_e32 v16, 64, v232, vcc
	v_cmp_le_u32_e32 vcc, v16, v17
	s_nop 1
	v_cndmask_b32_e32 v2, v249, v240, vcc
	v_or_b32_e32 v15, 1, v16
	v_cmp_le_u32_e32 vcc, v15, v17
	s_nop 1
	v_cndmask_b32_e32 v3, v249, v240, vcc
	v_or_b32_e32 v15, 2, v16
	v_cmp_le_u32_e32 vcc, v15, v17
	s_nop 1
	v_cndmask_b32_e32 v4, v249, v240, vcc
	v_or_b32_e32 v15, 3, v16
	v_cmp_le_u32_e32 vcc, v15, v17
	s_nop 1
	v_cndmask_b32_e32 v5, v249, v240, vcc
	v_or_b32_e32 v15, 4, v16
	v_cmp_le_u32_e32 vcc, v15, v17
	s_nop 1
	v_cndmask_b32_e32 v6, v249, v240, vcc
	v_or_b32_e32 v15, 5, v16
	v_cmp_le_u32_e32 vcc, v15, v17
	s_nop 1
	v_cndmask_b32_e32 v7, v249, v240, vcc
	v_or_b32_e32 v15, 6, v16
	v_cmp_le_u32_e32 vcc, v15, v17
	s_nop 1
	v_cndmask_b32_e32 v8, v249, v240, vcc
	v_or_b32_e32 v15, 7, v16
	v_cmp_le_u32_e32 vcc, v15, v17
	s_nop 1
	v_cndmask_b32_e32 v9, v249, v240, vcc
	s_nop 1
	v_mfma_f32_16x16x32_bf16 v[2:5], v[146:149], v[102:105], v[2:5]
	v_mfma_f32_16x16x32_bf16 v[6:9], v[154:157], v[102:105], v[6:9]
	s_branch .Lsel_qk2_Ba

; __device__ __forceinline__ f32x4v mfma16(bf16x8 a, bf16x8 b, f32x4v c) { return __builtin_amdgcn_mfma_f32_16x16x32_bf16(a, b, c, 0, 0, 0); }
; __device__ __forceinline__ void flash16_compute(bool domask, const bf16x8 (&kf)[4], const bf16x8 (&vf)[4], const bf16x8 (&q)[2], int x0, unsigned span, float& m, float& l, f32x4v (&O)[4]) {
;     f32x4v s0 = {0.f, 0.f, 0.f, 0.f}, s1 = {0.f, 0.f, 0.f, 0.f};
;     __builtin_amdgcn_s_setprio(1);
;     s0 = mfma16(kf[0], q[0], s0); s1 = mfma16(kf[2], q[0], s1);
;     s0 = mfma16(kf[1], q[1], s0); s1 = mfma16(kf[3], q[1], s1);
;     __builtin_amdgcn_s_setprio(0);
;     float sc[8] = {s0[0], s0[1], s0[2], s0[3], s1[0], s1[1], s1[2], s1[3]};
;     if (domask) {
; #pragma unroll
;         for (int j = 0; j < 8; ++j) sc[j] = ((unsigned)(x0 + j) <= span) ? sc[j] : -1e30f;
;     }
.Lsel_slow_Bb:
	s_and_b32 s10, s17, 0x7fff
	s_lshl_b32 s10, s10, 5
	v_subrev_u32_e32 v16, s10, v227
	s_nop 0
	v_cndmask_b32_e64 v16, v16, -1, vcc
	v_cmp_lt_i32_e32 vcc, -1, v16
	v_max_i32_e32 v17, 0, v16
	s_nop 0
	v_cndmask_b32_e32 v16, 64, v232, vcc
	v_cmp_le_u32_e32 vcc, v16, v17
	s_nop 1
	v_cndmask_b32_e32 v2, v249, v241, vcc
	v_or_b32_e32 v15, 1, v16
	v_cmp_le_u32_e32 vcc, v15, v17
	s_nop 1
	v_cndmask_b32_e32 v3, v249, v241, vcc
	v_or_b32_e32 v15, 2, v16
	v_cmp_le_u32_e32 vcc, v15, v17
	s_nop 1
	v_cndmask_b32_e32 v4, v249, v241, vcc
	v_or_b32_e32 v15, 3, v16
	v_cmp_le_u32_e32 vcc, v15, v17
	s_nop 1
	v_cndmask_b32_e32 v5, v249, v241, vcc
	v_or_b32_e32 v15, 4, v16
	v_cmp_le_u32_e32 vcc, v15, v17
	s_nop 1
	v_cndmask_b32_e32 v6, v249, v241, vcc
	v_or_b32_e32 v15, 5, v16
	v_cmp_le_u32_e32 vcc, v15, v17
	s_nop 1
	v_cndmask_b32_e32 v7, v249, v241, vcc
	v_or_b32_e32 v15, 6, v16
	v_cmp_le_u32_e32 vcc, v15, v17
	s_nop 1
	v_cndmask_b32_e32 v8, v249, v241, vcc
	v_or_b32_e32 v15, 7, v16
	v_cmp_le_u32_e32 vcc, v15, v17
	s_nop 1
	v_cndmask_b32_e32 v9, v249, v241, vcc
	s_nop 1
	v_mfma_f32_16x16x32_bf16 v[2:5], v[146:149], v[110:113], v[2:5]
	v_mfma_f32_16x16x32_bf16 v[6:9], v[154:157], v[110:113], v[6:9]
	s_branch .Lsel_qk2_Bb

; __device__ __forceinline__ f32x4v mfma16(bf16x8 a, bf16x8 b, f32x4v c) { return __builtin_amdgcn_mfma_f32_16x16x32_bf16(a, b, c, 0, 0, 0); }
; __device__ __forceinline__ void flash16_compute(bool domask, const bf16x8 (&kf)[4], const bf16x8 (&vf)[4], const bf16x8 (&q)[2], int x0, unsigned span, float& m, float& l, f32x4v (&O)[4]) {
;     f32x4v s0 = {0.f, 0.f, 0.f, 0.f}, s1 = {0.f, 0.f, 0.f, 0.f};
;     __builtin_amdgcn_s_setprio(1);
;     s0 = mfma16(kf[0], q[0], s0); s1 = mfma16(kf[2], q[0], s1);
;     s0 = mfma16(kf[1], q[1], s0); s1 = mfma16(kf[3], q[1], s1);
;     __builtin_amdgcn_s_setprio(0);
;     float sc[8] = {s0[0], s0[1], s0[2], s0[3], s1[0], s1[1], s1[2], s1[3]};
;     if (domask) {
; #pragma unroll
;         for (int j = 0; j < 8; ++j) sc[j] = ((unsigned)(x0 + j) <= span) ? sc[j] : -1e30f;
;     }
.Lsel_slow_Ca:
	s_and_b32 s10, s19, 0x7fff
	s_lshl_b32 s10, s10, 5
	v_subrev_u32_e32 v16, s10, v211
	s_nop 0
	v_cndmask_b32_e64 v16, v16, -1, vcc
	v_cmp_lt_i32_e32 vcc, -1, v16
	v_max_i32_e32 v17, 0, v16
	s_nop 0
	v_cndmask_b32_e32 v16, 64, v232, vcc
	v_cmp_le_u32_e32 vcc, v16, v17
	s_nop 1
	v_cndmask_b32_e32 v2, v249, v240, vcc
	v_or_b32_e32 v15, 1, v16
	v_cmp_le_u32_e32 vcc, v15, v17
	s_nop 1
	v_cndmask_b32_e32 v3, v249, v240, vcc
	v_or_b32_e32 v15, 2, v16
	v_cmp_le_u32_e32 vcc, v15, v17
	s_nop 1
	v_cndmask_b32_e32 v4, v249, v240, vcc
	v_or_b32_e32 v15, 3, v16
	v_cmp_le_u32_e32 vcc, v15, v17
	s_nop 1
	v_cndmask_b32_e32 v5, v249, v240, vcc
	v_or_b32_e32 v15, 4, v16
	v_cmp_le_u32_e32 vcc, v15, v17
	s_nop 1
	v_cndmask_b32_e32 v6, v249, v240, vcc
	v_or_b32_e32 v15, 5, v16
	v_cmp_le_u32_e32 vcc, v15, v17
	s_nop 1
	v_cndmask_b32_e32 v7, v249, v240, vcc
	v_or_b32_e32 v15, 6, v16
	v_cmp_le_u32_e32 vcc, v15, v17
	s_nop 1
	v_cndmask_b32_e32 v8, v249, v240, vcc
	v_or_b32_e32 v15, 7, v16
	v_cmp_le_u32_e32 vcc, v15, v17
	s_nop 1
	v_cndmask_b32_e32 v9, v249, v240, vcc
	s_nop 1
	v_mfma_f32_16x16x32_bf16 v[2:5], v[178:181], v[102:105], v[2:5]
	v_mfma_f32_16x16x32_bf16 v[6:9], v[186:189], v[102:105], v[6:9]
	s_branch .Lsel_qk2_Ca

; __device__ __forceinline__ f32x4v mfma16(bf16x8 a, bf16x8 b, f32x4v c) { return __builtin_amdgcn_mfma_f32_16x16x32_bf16(a, b, c, 0, 0, 0); }
; __device__ __forceinline__ void flash16_compute(bool domask, const bf16x8 (&kf)[4], const bf16x8 (&vf)[4], const bf16x8 (&q)[2], int x0, unsigned span, float& m, float& l, f32x4v (&O)[4]) {
;     f32x4v s0 = {0.f, 0.f, 0.f, 0.f}, s1 = {0.f, 0.f, 0.f, 0.f};
;     __builtin_amdgcn_s_setprio(1);
;     s0 = mfma16(kf[0], q[0], s0); s1 = mfma16(kf[2], q[0], s1);
;     s0 = mfma16(kf[1], q[1], s0); s1 = mfma16(kf[3], q[1], s1);
;     __builtin_amdgcn_s_setprio(0);
;     float sc[8] = {s0[0], s0[1], s0[2], s0[3], s1[0], s1[1], s1[2], s1[3]};
;     if (domask) {
; #pragma unroll
;         for (int j = 0; j < 8; ++j) sc[j] = ((unsigned)(x0 + j) <= span) ? sc[j] : -1e30f;
;     }
.Lsel_slow_Cb:
	s_and_b32 s10, s19, 0x7fff
	s_lshl_b32 s10, s10, 5
	v_subrev_u32_e32 v16, s10, v227
	s_nop 0
	v_cndmask_b32_e64 v16, v16, -1, vcc
	v_cmp_lt_i32_e32 vcc, -1, v16
	v_max_i32_e32 v17, 0, v16
	s_nop 0
	v_cndmask_b32_e32 v16, 64, v232, vcc
	v_cmp_le_u32_e32 vcc, v16, v17
	s_nop 1
	v_cndmask_b32_e32 v2, v249, v241, vcc
	v_or_b32_e32 v15, 1, v16
	v_cmp_le_u32_e32 vcc, v15, v17
	s_nop 1
	v_cndmask_b32_e32 v3, v249, v241, vcc
	v_or_b32_e32 v15, 2, v16
	v_cmp_le_u32_e32 vcc, v15, v17
	s_nop 1
	v_cndmask_b32_e32 v4, v249, v241, vcc
	v_or_b32_e32 v15, 3, v16
	v_cmp_le_u32_e32 vcc, v15, v17
	s_nop 1
	v_cndmask_b32_e32 v5, v249, v241, vcc
	v_or_b32_e32 v15, 4, v16
	v_cmp_le_u32_e32 vcc, v15, v17
	s_nop 1
	v_cndmask_b32_e32 v6, v249, v241, vcc
	v_or_b32_e32 v15, 5, v16
	v_cmp_le_u32_e32 vcc, v15, v17
	s_nop 1
	v_cndmask_b32_e32 v7, v249, v241, vcc
	v_or_b32_e32 v15, 6, v16
	v_cmp_le_u32_e32 vcc, v15, v17
	s_nop 1
	v_cndmask_b32_e32 v8, v249, v241, vcc
	v_or_b32_e32 v15, 7, v16
	v_cmp_le_u32_e32 vcc, v15, v17
	s_nop 1
	v_cndmask_b32_e32 v9, v249, v241, vcc
	s_nop 1
	v_mfma_f32_16x16x32_bf16 v[2:5], v[178:181], v[110:113], v[2:5]
	v_mfma_f32_16x16x32_bf16 v[6:9], v[186:189], v[110:113], v[6:9]
	s_branch .Lsel_qk2_Cb

; __device__ __forceinline__ f32x4v mfma16(bf16x8 a, bf16x8 b, f32x4v c) { return __builtin_amdgcn_mfma_f32_16x16x32_bf16(a, b, c, 0, 0, 0); }
; __device__ __forceinline__ void flash16_compute(bool domask, const bf16x8 (&kf)[4], const bf16x8 (&vf)[4], const bf16x8 (&q)[2], int x0, unsigned span, float& m, float& l, f32x4v (&O)[4]) {
;     f32x4v s0 = {0.f, 0.f, 0.f, 0.f}, s1 = {0.f, 0.f, 0.f, 0.f};
;     __builtin_amdgcn_s_setprio(1);
;     s0 = mfma16(kf[0], q[0], s0); s1 = mfma16(kf[2], q[0], s1);
;     s0 = mfma16(kf[1], q[1], s0); s1 = mfma16(kf[3], q[1], s1);
;     __builtin_amdgcn_s_setprio(0);
;     float sc[8] = {s0[0], s0[1], s0[2], s0[3], s1[0], s1[1], s1[2], s1[3]};
;     if (domask) {
; #pragma unroll
;         for (int j = 0; j < 8; ++j) sc[j] = ((unsigned)(x0 + j) <= span) ? sc[j] : -1e30f;
;     }
.Lsel_slow_Da:
	s_and_b32 s10, s4, 0x7fff
	s_lshl_b32 s10, s10, 5
	v_subrev_u32_e32 v16, s10, v211
	s_nop 0
	v_cndmask_b32_e64 v16, v16, -1, vcc
	v_cmp_lt_i32_e32 vcc, -1, v16
	v_max_i32_e32 v17, 0, v16
	s_nop 0
	v_cndmask_b32_e32 v16, 64, v232, vcc
	v_cmp_le_u32_e32 vcc, v16, v17
	s_nop 1
	v_cndmask_b32_e32 v2, v249, v240, vcc
	v_or_b32_e32 v15, 1, v16
	v_cmp_le_u32_e32 vcc, v15, v17
	s_nop 1
	v_cndmask_b32_e32 v3, v249, v240, vcc
	v_or_b32_e32 v15, 2, v16
	v_cmp_le_u32_e32 vcc, v15, v17
	s_nop 1
	v_cndmask_b32_e32 v4, v249, v240, vcc
	v_or_b32_e32 v15, 3, v16
	v_cmp_le_u32_e32 vcc, v15, v17
	s_nop 1
	v_cndmask_b32_e32 v5, v249, v240, vcc
	v_or_b32_e32 v15, 4, v16
	v_cmp_le_u32_e32 vcc, v15, v17
	s_nop 1
	v_cndmask_b32_e32 v6, v249, v240, vcc
	v_or_b32_e32 v15, 5, v16
	v_cmp_le_u32_e32 vcc, v15, v17
	s_nop 1
	v_cndmask_b32_e32 v7, v249, v240, vcc
	v_or_b32_e32 v15, 6, v16
	v_cmp_le_u32_e32 vcc, v15, v17
	s_nop 1
	v_cndmask_b32_e32 v8, v249, v240, vcc
	v_or_b32_e32 v15, 7, v16
	v_cmp_le_u32_e32 vcc, v15, v17
	s_nop 1
	v_cndmask_b32_e32 v9, v249, v240, vcc
	s_nop 1
	v_mfma_f32_16x16x32_bf16 v[2:5], v[62:65], v[102:105], v[2:5]
	v_mfma_f32_16x16x32_bf16 v[6:9], v[70:73], v[102:105], v[6:9]
	s_branch .Lsel_qk2_Da

; __device__ __forceinline__ f32x4v mfma16(bf16x8 a, bf16x8 b, f32x4v c) { return __builtin_amdgcn_mfma_f32_16x16x32_bf16(a, b, c, 0, 0, 0); }
; __device__ __forceinline__ void flash16_compute(bool domask, const bf16x8 (&kf)[4], const bf16x8 (&vf)[4], const bf16x8 (&q)[2], int x0, unsigned span, float& m, float& l, f32x4v (&O)[4]) {
;     f32x4v s0 = {0.f, 0.f, 0.f, 0.f}, s1 = {0.f, 0.f, 0.f, 0.f};
;     __builtin_amdgcn_s_setprio(1);
;     s0 = mfma16(kf[0], q[0], s0); s1 = mfma16(kf[2], q[0], s1);
;     s0 = mfma16(kf[1], q[1], s0); s1 = mfma16(kf[3], q[1], s1);
;     __builtin_amdgcn_s_setprio(0);
;     float sc[8] = {s0[0], s0[1], s0[2], s0[3], s1[0], s1[1], s1[2], s1[3]};
;     if (domask) {
; #pragma unroll
;         for (int j = 0; j < 8; ++j) sc[j] = ((unsigned)(x0 + j) <= span) ? sc[j] : -1e30f;
;     }
.Lsel_slow_Db:
	s_and_b32 s10, s4, 0x7fff
	s_lshl_b32 s10, s10, 5
	v_subrev_u32_e32 v16, s10, v227
	s_nop 0
	v_cndmask_b32_e64 v16, v16, -1, vcc
	v_cmp_lt_i32_e32 vcc, -1, v16
	v_max_i32_e32 v17, 0, v16
	s_nop 0
	v_cndmask_b32_e32 v16, 64, v232, vcc
	v_cmp_le_u32_e32 vcc, v16, v17
	s_nop 1
	v_cndmask_b32_e32 v2, v249, v241, vcc
	v_or_b32_e32 v15, 1, v16
	v_cmp_le_u32_e32 vcc, v15, v17
	s_nop 1
	v_cndmask_b32_e32 v3, v249, v241, vcc
	v_or_b32_e32 v15, 2, v16
	v_cmp_le_u32_e32 vcc, v15, v17
	s_nop 1
	v_cndmask_b32_e32 v4, v249, v241, vcc
	v_or_b32_e32 v15, 3, v16
	v_cmp_le_u32_e32 vcc, v15, v17
	s_nop 1
	v_cndmask_b32_e32 v5, v249, v241, vcc
	v_or_b32_e32 v15, 4, v16
	v_cmp_le_u32_e32 vcc, v15, v17
	s_nop 1
	v_cndmask_b32_e32 v6, v249, v241, vcc
	v_or_b32_e32 v15, 5, v16
	v_cmp_le_u32_e32 vcc, v15, v17
	s_nop 1
	v_cndmask_b32_e32 v7, v249, v241, vcc
	v_or_b32_e32 v15, 6, v16
	v_cmp_le_u32_e32 vcc, v15, v17
	s_nop 1
	v_cndmask_b32_e32 v8, v249, v241, vcc
	v_or_b32_e32 v15, 7, v16
	v_cmp_le_u32_e32 vcc, v15, v17
	s_nop 1
	v_cndmask_b32_e32 v9, v249, v241, vcc
	s_nop 1
	v_mfma_f32_16x16x32_bf16 v[2:5], v[62:65], v[110:113], v[2:5]
	v_mfma_f32_16x16x32_bf16 v[6:9], v[70:73], v[110:113], v[6:9]
	s_branch .Lsel_qk2_Db

; __device__ __forceinline__ float bf_lo(unsigned u) { return __uint_as_float(u << 16); }
; __device__ __forceinline__ float bf_hi(unsigned u) { return __uint_as_float(u & 0xffff0000u); }
; __device__ __forceinline__ void norm_phase(const Ctx& C, int w0, int nw, const float* xin, float* xout, const bf16_t* y, bf16_t* h, const float* gpost, const float* gpre, float coef) {
;     for (int m0 = w0; m0 < T_; m0 += 2 * nw) {
;         f32x4 xv[2][4]; u32x2 yw[2][4];
; #pragma unroll
;         for (int r = 0; r < 2; ++r) { const int m = (m0 + r * nw < T_) ? m0 + r * nw : m0; const f32x4* xr = (const f32x4*)(xin + (size_t)m * DM) + C.lane; const u32x2* yr = (const u32x2*)(y + (size_t)m * DM) + C.lane;
; #pragma unroll
;             for (int j = 0; j < 4; ++j) { xv[r][j] = xr[64 * j]; yw[r][j] = yr[64 * j]; } }
; #pragma unroll
;         for (int r = 0; r < 2; ++r) {
;             const int m = m0 + r * nw; if (m >= T_) break;
;             f32x4 yv[4]; float s = 0.f;
; #pragma unroll
;             for (int j = 0; j < 4; ++j) { const u32x2 w = yw[r][j]; yv[j] = (f32x4){bf_lo(w.x), bf_hi(w.x), bf_lo(w.y), bf_hi(w.y)};
;                 s += (yv[j].x * yv[j].x + yv[j].y * yv[j].y) + (yv[j].z * yv[j].z + yv[j].w * yv[j].w); }
;             const float rs = rsqrtf(wave_sum(s) * (1.f / DM) + EPS) * coef; float s2 = 0.f;
;             f32x4* xo = (f32x4*)(xout + (size_t)m * DM) + C.lane;
; #pragma unroll
;             for (int j = 0; j < 4; ++j) { const f32x4 gg = ((const f32x4*)gpost)[C.lane + 64 * j]; xv[r][j] = xv[r][j] + yv[j] * gg * rs; xo[64 * j] = xv[r][j];
;                 s2 += (xv[r][j].x * xv[r][j].x + xv[r][j].y * xv[r][j].y) + (xv[r][j].z * xv[r][j].z + xv[r][j].w * xv[r][j].w); }
.LBB0_1197:
	global_load_dwordx4 v[100:103], v[38:39], off
	global_load_dwordx4 v[104:107], v[38:39], off offset:1024
	global_load_dwordx4 v[108:111], v[38:39], off offset:2048
	global_load_dwordx4 v[112:115], v[38:39], off offset:3072
	s_and_b64 vcc, exec, s[8:9]
	s_cbranch_vccz .Ln11_loop
	global_load_dwordx4 v[116:119], v[42:43], off
	global_load_dwordx4 v[120:123], v[42:43], off offset:1024
	global_load_dwordx4 v[124:127], v[42:43], off offset:2048
	global_load_dwordx4 v[128:131], v[42:43], off offset:3072
.Ln11_loop:
	s_ashr_i32 s23, s22, 31
	s_add_i32 s12, s22, s70
	s_cmp_lt_i32 s12, 0x8000
	s_cselect_b64 s[18:19], -1, 0
	s_cselect_b32 s0, s12, s22
	s_ashr_i32 s1, s0, 31
	s_lshl_b64 s[2:3], s[22:23], 11
	v_lshl_add_u64 v[4:5], v[36:37], 0, s[2:3]
	v_lshl_add_u64 v[10:11], v[40:41], 0, s[2:3]
	s_lshl_b64 s[2:3], s[22:23], 12
	v_lshl_add_u64 v[2:3], v[34:35], 0, s[2:3]
	s_lshl_b64 s[2:3], s[0:1], 11
	v_lshl_add_u64 v[8:9], v[36:37], 0, s[2:3]
	v_lshl_add_u64 v[12:13], v[40:41], 0, s[2:3]
	s_lshl_b64 s[2:3], s[0:1], 12
	v_lshl_add_u64 v[6:7], v[34:35], 0, s[2:3]
	global_load_dwordx2 v[148:149], v[4:5], off
	global_load_dwordx2 v[150:151], v[4:5], off offset:512
	global_load_dwordx2 v[152:153], v[4:5], off offset:1024
	global_load_dwordx2 v[154:155], v[4:5], off offset:1536
	global_load_dwordx4 v[132:135], v[2:3], off
	global_load_dwordx4 v[136:139], v[2:3], off offset:1024
	global_load_dwordx4 v[140:143], v[2:3], off offset:2048
	global_load_dwordx4 v[144:147], v[2:3], off offset:3072
	global_load_dwordx2 v[172:173], v[8:9], off
	global_load_dwordx2 v[174:175], v[8:9], off offset:512
	global_load_dwordx2 v[176:177], v[8:9], off offset:1024
	global_load_dwordx2 v[178:179], v[8:9], off offset:1536
	global_load_dwordx4 v[156:159], v[6:7], off
	global_load_dwordx4 v[160:163], v[6:7], off offset:1024
	global_load_dwordx4 v[164:167], v[6:7], off offset:2048
	global_load_dwordx4 v[168:171], v[6:7], off offset:3072
	s_waitcnt vmcnt(12)
	v_lshlrev_b32_e32 v44, 16, v148
	v_and_b32_e32 v45, 0xffff0000, v148
	v_lshlrev_b32_e32 v46, 16, v149
	v_and_b32_e32 v47, 0xffff0000, v149
	v_lshlrev_b32_e32 v48, 16, v150
	v_and_b32_e32 v49, 0xffff0000, v150
	v_lshlrev_b32_e32 v50, 16, v151
	v_and_b32_e32 v51, 0xffff0000, v151
	v_lshlrev_b32_e32 v52, 16, v152
	v_and_b32_e32 v53, 0xffff0000, v152
	v_lshlrev_b32_e32 v54, 16, v153
	v_and_b32_e32 v55, 0xffff0000, v153
	v_lshlrev_b32_e32 v56, 16, v154
	v_and_b32_e32 v57, 0xffff0000, v154
	v_lshlrev_b32_e32 v58, 16, v155
	v_and_b32_e32 v59, 0xffff0000, v155
	v_mul_f32_e32 v14, v45, v45
	v_mul_f32_e32 v15, v47, v47
	v_mul_f32_e32 v16, v49, v49
	v_mul_f32_e32 v17, v51, v51
	v_mul_f32_e32 v18, v53, v53
	v_mul_f32_e32 v19, v55, v55
	v_mul_f32_e32 v20, v57, v57
	v_mul_f32_e32 v21, v59, v59
	v_fmac_f32_e32 v14, v44, v44
	v_fmac_f32_e32 v15, v46, v46
	v_fmac_f32_e32 v16, v48, v48
	v_fmac_f32_e32 v17, v50, v50
	v_fmac_f32_e32 v18, v52, v52
	v_fmac_f32_e32 v19, v54, v54
	v_fmac_f32_e32 v20, v56, v56
	v_fmac_f32_e32 v21, v58, v58
	v_add_f32_e32 v14, v14, v15
	v_add_f32_e32 v16, v16, v17
	v_add_f32_e32 v18, v18, v19
	v_add_f32_e32 v20, v20, v21
	v_add_f32_e32 v22, v14, v16
	v_add_f32_e32 v22, v18, v22
	v_add_f32_e32 v22, v20, v22
	s_nop 1
	v_add_f32_dpp v22, v22, v22 quad_perm:[1,0,3,2] row_mask:0xf bank_mask:0xf bound_ctrl:1
	s_nop 1
	v_add_f32_dpp v22, v22, v22 quad_perm:[2,3,0,1] row_mask:0xf bank_mask:0xf bound_ctrl:1
	s_nop 1
	v_add_f32_dpp v22, v22, v22 row_half_mirror row_mask:0xf bank_mask:0xf bound_ctrl:1
	s_nop 1
	v_add_f32_dpp v22, v22, v22 row_mirror row_mask:0xf bank_mask:0xf bound_ctrl:1
	v_mov_b32_e32 v23, v22
	s_nop 1
	v_permlane16_swap_b32_e32 v22, v23
	v_add_f32_e32 v22, v22, v23
	v_mov_b32_e32 v23, v22
	s_nop 1
	v_permlane32_swap_b32_e32 v22, v23
	v_add_f32_e32 v22, v22, v23
	v_fmamk_f32 v22, v22, 0x3a800000, v248
	v_mul_f32_e32 v23, 0x4b800000, v22
	v_cmp_gt_f32_e32 vcc, s64, v22
	s_nop 1
	v_cndmask_b32_e32 v22, v22, v23, vcc
	v_rsq_f32_e32 v22, v22
	s_nop 0
	v_mul_f32_e32 v23, 0x45800000, v22
	v_cndmask_b32_e32 v22, v22, v23, vcc
	s_waitcnt vmcnt(8)
	v_mul_f32_e32 v24, v44, v100
	v_mul_f32_e32 v25, v45, v101
	v_mul_f32_e32 v26, v46, v102
	v_mul_f32_e32 v27, v47, v103
	v_fmac_f32_e32 v132, v24, v22
	v_fmac_f32_e32 v133, v25, v22
	v_fmac_f32_e32 v134, v26, v22
	v_fmac_f32_e32 v135, v27, v22
	v_mul_f32_e32 v24, v48, v104
	v_mul_f32_e32 v25, v49, v105
	v_mul_f32_e32 v26, v50, v106
	v_mul_f32_e32 v27, v51, v107
	v_fmac_f32_e32 v136, v24, v22
	v_fmac_f32_e32 v137, v25, v22
	v_fmac_f32_e32 v138, v26, v22
	v_fmac_f32_e32 v139, v27, v22
	v_mul_f32_e32 v24, v52, v108
	v_mul_f32_e32 v25, v53, v109
	v_mul_f32_e32 v26, v54, v110
	v_mul_f32_e32 v27, v55, v111
	v_fmac_f32_e32 v140, v24, v22
	v_fmac_f32_e32 v141, v25, v22
	v_fmac_f32_e32 v142, v26, v22
	v_fmac_f32_e32 v143, v27, v22
	v_mul_f32_e32 v24, v56, v112
	v_mul_f32_e32 v25, v57, v113
	v_mul_f32_e32 v26, v58, v114
	v_mul_f32_e32 v27, v59, v115
	v_fmac_f32_e32 v144, v24, v22
	v_fmac_f32_e32 v145, v25, v22
	v_fmac_f32_e32 v146, v26, v22
	v_fmac_f32_e32 v147, v27, v22
	s_and_b64 vcc, exec, s[8:9]
	s_cbranch_vccz .Ln11_noh_A
; __device__ __forceinline__ unsigned cvt_pk_bf16(float lo, float hi) { f32x2_t v = {lo, hi}; bf16x2_t b = __builtin_convertvector(v, bf16x2_t); return __builtin_bit_cast(unsigned, b); }
; __device__ __forceinline__ float bf_lo(unsigned u) { return __uint_as_float(u << 16); }
; __device__ __forceinline__ float bf_hi(unsigned u) { return __uint_as_float(u & 0xffff0000u); }
; __device__ __forceinline__ void norm_phase(const Ctx& C, int w0, int nw, const float* xin, float* xout, const bf16_t* y, bf16_t* h, const float* gpost, const float* gpre, float coef) {
;     ...
;         for (int r = 0; r < 2; ++r) {
;             const int m = m0 + r * nw; if (m >= T_) break;
;             f32x4 yv[4]; float s = 0.f;
; #pragma unroll
;             for (int j = 0; j < 4; ++j) { const u32x2 w = yw[r][j]; yv[j] = (f32x4){bf_lo(w.x), bf_hi(w.x), bf_lo(w.y), bf_hi(w.y)};
;                 s += (yv[j].x * yv[j].x + yv[j].y * yv[j].y) + (yv[j].z * yv[j].z + yv[j].w * yv[j].w); }
;             const float rs = rsqrtf(wave_sum(s) * (1.f / DM) + EPS) * coef; float s2 = 0.f;
;             f32x4* xo = (f32x4*)(xout + (size_t)m * DM) + C.lane;
; #pragma unroll
;             for (int j = 0; j < 4; ++j) { const f32x4 gg = ((const f32x4*)gpost)[C.lane + 64 * j]; xv[r][j] = xv[r][j] + yv[j] * gg * rs; xo[64 * j] = xv[r][j];
;                 s2 += (xv[r][j].x * xv[r][j].x + xv[r][j].y * xv[r][j].y) + (xv[r][j].z * xv[r][j].z + xv[r][j].w * xv[r][j].w); }
;             if (gpre) {
;                 const float r2 = rsqrtf(wave_sum(s2) * (1.f / DM) + EPS);
;                 u32x2* o = (u32x2*)(h + (size_t)m * DM) + C.lane;
; #pragma unroll
;                 for (int j = 0; j < 4; ++j) { const f32x4 gg = ((const f32x4*)gpre)[C.lane + 64 * j]; u32x2 w; w.x = cvt_pk_bf16(xv[r][j].x * r2 * gg.x, xv[r][j].y * r2 * gg.y); w.y = cvt_pk_bf16(xv[r][j].z * r2 * gg.z, xv[r][j].w * r2 * gg.w); o[64 * j] = w; }
;             }
	v_mul_f32_e32 v14, v133, v133
	v_mul_f32_e32 v15, v135, v135
	v_mul_f32_e32 v16, v137, v137
	v_mul_f32_e32 v17, v139, v139
	v_mul_f32_e32 v18, v141, v141
	v_mul_f32_e32 v19, v143, v143
	v_mul_f32_e32 v20, v145, v145
	v_mul_f32_e32 v21, v147, v147
	v_fmac_f32_e32 v14, v132, v132
	v_fmac_f32_e32 v15, v134, v134
	v_fmac_f32_e32 v16, v136, v136
	v_fmac_f32_e32 v17, v138, v138
	v_fmac_f32_e32 v18, v140, v140
	v_fmac_f32_e32 v19, v142, v142
	v_fmac_f32_e32 v20, v144, v144
	v_fmac_f32_e32 v21, v146, v146
	v_add_f32_e32 v14, v14, v15
	v_add_f32_e32 v16, v16, v17
	v_add_f32_e32 v18, v18, v19
	v_add_f32_e32 v20, v20, v21
	v_add_f32_e32 v22, v14, v16
	v_add_f32_e32 v22, v18, v22
	v_add_f32_e32 v22, v20, v22
	s_nop 1
	v_add_f32_dpp v22, v22, v22 quad_perm:[1,0,3,2] row_mask:0xf bank_mask:0xf bound_ctrl:1
	s_nop 1
	v_add_f32_dpp v22, v22, v22 quad_perm:[2,3,0,1] row_mask:0xf bank_mask:0xf bound_ctrl:1
	s_nop 1
	v_add_f32_dpp v22, v22, v22 row_half_mirror row_mask:0xf bank_mask:0xf bound_ctrl:1
	s_nop 1
	v_add_f32_dpp v22, v22, v22 row_mirror row_mask:0xf bank_mask:0xf bound_ctrl:1
	v_mov_b32_e32 v23, v22
	s_nop 1
	v_permlane16_swap_b32_e32 v22, v23
	v_add_f32_e32 v22, v22, v23
	v_mov_b32_e32 v23, v22
	s_nop 1
	v_permlane32_swap_b32_e32 v22, v23
	v_add_f32_e32 v22, v22, v23
	v_fmamk_f32 v22, v22, 0x3a800000, v248
	v_mul_f32_e32 v23, 0x4b800000, v22
	v_cmp_gt_f32_e32 vcc, s64, v22
	s_nop 1
	v_cndmask_b32_e32 v22, v22, v23, vcc
	v_rsq_f32_e32 v22, v22
	s_nop 0
	v_mul_f32_e32 v23, 0x45800000, v22
	v_cndmask_b32_e32 v22, v22, v23, vcc
	v_mul_f32_e32 v24, v132, v22
	v_mul_f32_e32 v25, v133, v22
	v_mul_f32_e32 v26, v134, v22
	v_mul_f32_e32 v27, v135, v22
	v_mul_f32_e32 v24, v116, v24
	v_mul_f32_e32 v25, v117, v25
	v_mul_f32_e32 v26, v118, v26
	v_mul_f32_e32 v27, v119, v27
	v_cvt_pk_bf16_f32 v180, v24, v25
	v_cvt_pk_bf16_f32 v181, v26, v27
	v_mul_f32_e32 v24, v136, v22
	v_mul_f32_e32 v25, v137, v22
	v_mul_f32_e32 v26, v138, v22
	v_mul_f32_e32 v27, v139, v22
	v_mul_f32_e32 v24, v120, v24
	v_mul_f32_e32 v25, v121, v25
	v_mul_f32_e32 v26, v122, v26
	v_mul_f32_e32 v27, v123, v27
	v_cvt_pk_bf16_f32 v182, v24, v25
	v_cvt_pk_bf16_f32 v183, v26, v27
	v_mul_f32_e32 v24, v140, v22
	v_mul_f32_e32 v25, v141, v22
	v_mul_f32_e32 v26, v142, v22
	v_mul_f32_e32 v27, v143, v22
	v_mul_f32_e32 v24, v124, v24
	v_mul_f32_e32 v25, v125, v25
	v_mul_f32_e32 v26, v126, v26
	v_mul_f32_e32 v27, v127, v27
	v_cvt_pk_bf16_f32 v184, v24, v25
	v_cvt_pk_bf16_f32 v185, v26, v27
	v_mul_f32_e32 v24, v144, v22
	v_mul_f32_e32 v25, v145, v22
	v_mul_f32_e32 v26, v146, v22
	v_mul_f32_e32 v27, v147, v22
	v_mul_f32_e32 v24, v128, v24
	v_mul_f32_e32 v25, v129, v25
	v_mul_f32_e32 v26, v130, v26
	v_mul_f32_e32 v27, v131, v27
	v_cvt_pk_bf16_f32 v186, v24, v25
	v_cvt_pk_bf16_f32 v187, v26, v27
.Ln11_noh_A:
	s_and_b64 vcc, exec, s[18:19]
	s_cbranch_vccz .Ln11_skipB
	s_waitcnt vmcnt(4)
	v_lshlrev_b32_e32 v44, 16, v172
	v_and_b32_e32 v45, 0xffff0000, v172
	v_lshlrev_b32_e32 v46, 16, v173
	v_and_b32_e32 v47, 0xffff0000, v173
	v_lshlrev_b32_e32 v48, 16, v174
	v_and_b32_e32 v49, 0xffff0000, v174
	v_lshlrev_b32_e32 v50, 16, v175
	v_and_b32_e32 v51, 0xffff0000, v175
	v_lshlrev_b32_e32 v52, 16, v176
	v_and_b32_e32 v53, 0xffff0000, v176
	v_lshlrev_b32_e32 v54, 16, v177
	v_and_b32_e32 v55, 0xffff0000, v177
	v_lshlrev_b32_e32 v56, 16, v178
	v_and_b32_e32 v57, 0xffff0000, v178
	v_lshlrev_b32_e32 v58, 16, v179
	v_and_b32_e32 v59, 0xffff0000, v179
	v_mul_f32_e32 v14, v45, v45
	v_mul_f32_e32 v15, v47, v47
	v_mul_f32_e32 v16, v49, v49
	v_mul_f32_e32 v17, v51, v51
	v_mul_f32_e32 v18, v53, v53
	v_mul_f32_e32 v19, v55, v55
	v_mul_f32_e32 v20, v57, v57
	v_mul_f32_e32 v21, v59, v59
	v_fmac_f32_e32 v14, v44, v44
	v_fmac_f32_e32 v15, v46, v46
	v_fmac_f32_e32 v16, v48, v48
	v_fmac_f32_e32 v17, v50, v50
	v_fmac_f32_e32 v18, v52, v52
	v_fmac_f32_e32 v19, v54, v54
	v_fmac_f32_e32 v20, v56, v56
	v_fmac_f32_e32 v21, v58, v58
	v_add_f32_e32 v14, v14, v15
	v_add_f32_e32 v16, v16, v17
	v_add_f32_e32 v18, v18, v19
	v_add_f32_e32 v20, v20, v21
	v_add_f32_e32 v22, v14, v16
	v_add_f32_e32 v22, v18, v22
	v_add_f32_e32 v22, v20, v22
	s_nop 1
	v_add_f32_dpp v22, v22, v22 quad_perm:[1,0,3,2] row_mask:0xf bank_mask:0xf bound_ctrl:1
	s_nop 1
	v_add_f32_dpp v22, v22, v22 quad_perm:[2,3,0,1] row_mask:0xf bank_mask:0xf bound_ctrl:1
	s_nop 1
	v_add_f32_dpp v22, v22, v22 row_half_mirror row_mask:0xf bank_mask:0xf bound_ctrl:1
	s_nop 1
	v_add_f32_dpp v22, v22, v22 row_mirror row_mask:0xf bank_mask:0xf bound_ctrl:1
	v_mov_b32_e32 v23, v22
	s_nop 1
	v_permlane16_swap_b32_e32 v22, v23
	v_add_f32_e32 v22, v22, v23
	v_mov_b32_e32 v23, v22
	s_nop 1
	v_permlane32_swap_b32_e32 v22, v23
	v_add_f32_e32 v22, v22, v23
	v_fmamk_f32 v22, v22, 0x3a800000, v248
	v_mul_f32_e32 v23, 0x4b800000, v22
	v_cmp_gt_f32_e32 vcc, s64, v22
	s_nop 1
	v_cndmask_b32_e32 v22, v22, v23, vcc
	v_rsq_f32_e32 v22, v22
	s_nop 0
	v_mul_f32_e32 v23, 0x45800000, v22
	v_cndmask_b32_e32 v22, v22, v23, vcc
	s_waitcnt vmcnt(0)
	v_mul_f32_e32 v24, v44, v100
	v_mul_f32_e32 v25, v45, v101
	v_mul_f32_e32 v26, v46, v102
	v_mul_f32_e32 v27, v47, v103
	v_fmac_f32_e32 v156, v24, v22
	v_fmac_f32_e32 v157, v25, v22
	v_fmac_f32_e32 v158, v26, v22
	v_fmac_f32_e32 v159, v27, v22
	v_mul_f32_e32 v24, v48, v104
	v_mul_f32_e32 v25, v49, v105
	v_mul_f32_e32 v26, v50, v106
	v_mul_f32_e32 v27, v51, v107
	v_fmac_f32_e32 v160, v24, v22
	v_fmac_f32_e32 v161, v25, v22
	v_fmac_f32_e32 v162, v26, v22
	v_fmac_f32_e32 v163, v27, v22
	v_mul_f32_e32 v24, v52, v108
	v_mul_f32_e32 v25, v53, v109
	v_mul_f32_e32 v26, v54, v110
	v_mul_f32_e32 v27, v55, v111
	v_fmac_f32_e32 v164, v24, v22
	v_fmac_f32_e32 v165, v25, v22
	v_fmac_f32_e32 v166, v26, v22
	v_fmac_f32_e32 v167, v27, v22
	v_mul_f32_e32 v24, v56, v112
	v_mul_f32_e32 v25, v57, v113
	v_mul_f32_e32 v26, v58, v114
	v_mul_f32_e32 v27, v59, v115
	v_fmac_f32_e32 v168, v24, v22
	v_fmac_f32_e32 v169, v25, v22
	v_fmac_f32_e32 v170, v26, v22
	v_fmac_f32_e32 v171, v27, v22
	s_and_b64 vcc, exec, s[8:9]
	s_cbranch_vccz .Ln11_noh_B
; __device__ __forceinline__ unsigned cvt_pk_bf16(float lo, float hi) { f32x2_t v = {lo, hi}; bf16x2_t b = __builtin_convertvector(v, bf16x2_t); return __builtin_bit_cast(unsigned, b); }
; __device__ __forceinline__ void norm_phase(const Ctx& C, int w0, int nw, const float* xin, float* xout, const bf16_t* y, bf16_t* h, const float* gpost, const float* gpre, float coef) {
;     ...
;             const float rs = rsqrtf(wave_sum(s) * (1.f / DM) + EPS) * coef; float s2 = 0.f;
;             f32x4* xo = (f32x4*)(xout + (size_t)m * DM) + C.lane;
; #pragma unroll
;             for (int j = 0; j < 4; ++j) { const f32x4 gg = ((const f32x4*)gpost)[C.lane + 64 * j]; xv[r][j] = xv[r][j] + yv[j] * gg * rs; xo[64 * j] = xv[r][j];
;                 s2 += (xv[r][j].x * xv[r][j].x + xv[r][j].y * xv[r][j].y) + (xv[r][j].z * xv[r][j].z + xv[r][j].w * xv[r][j].w); }
;             if (gpre) {
;                 const float r2 = rsqrtf(wave_sum(s2) * (1.f / DM) + EPS);
;                 u32x2* o = (u32x2*)(h + (size_t)m * DM) + C.lane;
; #pragma unroll
;                 for (int j = 0; j < 4; ++j) { const f32x4 gg = ((const f32x4*)gpre)[C.lane + 64 * j]; u32x2 w; w.x = cvt_pk_bf16(xv[r][j].x * r2 * gg.x, xv[r][j].y * r2 * gg.y); w.y = cvt_pk_bf16(xv[r][j].z * r2 * gg.z, xv[r][j].w * r2 * gg.w); o[64 * j] = w; }
;             }
;         }
;     }
	v_mul_f32_e32 v14, v157, v157
	v_mul_f32_e32 v15, v159, v159
	v_mul_f32_e32 v16, v161, v161
	v_mul_f32_e32 v17, v163, v163
	v_mul_f32_e32 v18, v165, v165
	v_mul_f32_e32 v19, v167, v167
	v_mul_f32_e32 v20, v169, v169
	v_mul_f32_e32 v21, v171, v171
	v_fmac_f32_e32 v14, v156, v156
	v_fmac_f32_e32 v15, v158, v158
	v_fmac_f32_e32 v16, v160, v160
	v_fmac_f32_e32 v17, v162, v162
	v_fmac_f32_e32 v18, v164, v164
	v_fmac_f32_e32 v19, v166, v166
	v_fmac_f32_e32 v20, v168, v168
	v_fmac_f32_e32 v21, v170, v170
	v_add_f32_e32 v14, v14, v15
	v_add_f32_e32 v16, v16, v17
	v_add_f32_e32 v18, v18, v19
	v_add_f32_e32 v20, v20, v21
	v_add_f32_e32 v22, v14, v16
	v_add_f32_e32 v22, v18, v22
	v_add_f32_e32 v22, v20, v22
	s_nop 1
	v_add_f32_dpp v22, v22, v22 quad_perm:[1,0,3,2] row_mask:0xf bank_mask:0xf bound_ctrl:1
	s_nop 1
	v_add_f32_dpp v22, v22, v22 quad_perm:[2,3,0,1] row_mask:0xf bank_mask:0xf bound_ctrl:1
	s_nop 1
	v_add_f32_dpp v22, v22, v22 row_half_mirror row_mask:0xf bank_mask:0xf bound_ctrl:1
	s_nop 1
	v_add_f32_dpp v22, v22, v22 row_mirror row_mask:0xf bank_mask:0xf bound_ctrl:1
	v_mov_b32_e32 v23, v22
	s_nop 1
	v_permlane16_swap_b32_e32 v22, v23
	v_add_f32_e32 v22, v22, v23
	v_mov_b32_e32 v23, v22
	s_nop 1
	v_permlane32_swap_b32_e32 v22, v23
	v_add_f32_e32 v22, v22, v23
	v_fmamk_f32 v22, v22, 0x3a800000, v248
	v_mul_f32_e32 v23, 0x4b800000, v22
	v_cmp_gt_f32_e32 vcc, s64, v22
	s_nop 1
	v_cndmask_b32_e32 v22, v22, v23, vcc
	v_rsq_f32_e32 v22, v22
	s_nop 0
	v_mul_f32_e32 v23, 0x45800000, v22
	v_cndmask_b32_e32 v22, v22, v23, vcc
	v_mul_f32_e32 v24, v156, v22
	v_mul_f32_e32 v25, v157, v22
	v_mul_f32_e32 v26, v158, v22
	v_mul_f32_e32 v27, v159, v22
	v_mul_f32_e32 v24, v116, v24
	v_mul_f32_e32 v25, v117, v25
	v_mul_f32_e32 v26, v118, v26
	v_mul_f32_e32 v27, v119, v27
	v_cvt_pk_bf16_f32 v188, v24, v25
	v_cvt_pk_bf16_f32 v189, v26, v27
	v_mul_f32_e32 v24, v160, v22
	v_mul_f32_e32 v25, v161, v22
	v_mul_f32_e32 v26, v162, v22
	v_mul_f32_e32 v27, v163, v22
	v_mul_f32_e32 v24, v120, v24
	v_mul_f32_e32 v25, v121, v25
	v_mul_f32_e32 v26, v122, v26
	v_mul_f32_e32 v27, v123, v27
	v_cvt_pk_bf16_f32 v190, v24, v25
	v_cvt_pk_bf16_f32 v191, v26, v27
	v_mul_f32_e32 v24, v164, v22
	v_mul_f32_e32 v25, v165, v22
	v_mul_f32_e32 v26, v166, v22
	v_mul_f32_e32 v27, v167, v22
	v_mul_f32_e32 v24, v124, v24
	v_mul_f32_e32 v25, v125, v25
	v_mul_f32_e32 v26, v126, v26
	v_mul_f32_e32 v27, v127, v27
	v_cvt_pk_bf16_f32 v192, v24, v25
	v_cvt_pk_bf16_f32 v193, v26, v27
	v_mul_f32_e32 v24, v168, v22
	v_mul_f32_e32 v25, v169, v22
	v_mul_f32_e32 v26, v170, v22
	v_mul_f32_e32 v27, v171, v22
	v_mul_f32_e32 v24, v128, v24
	v_mul_f32_e32 v25, v129, v25
	v_mul_f32_e32 v26, v130, v26
	v_mul_f32_e32 v27, v131, v27
	v_cvt_pk_bf16_f32 v194, v24, v25
	v_cvt_pk_bf16_f32 v195, v26, v27
.Ln11_noh_B:
.Ln11_skipB:
	global_store_dwordx4 v[2:3], v[132:135], off
	global_store_dwordx4 v[2:3], v[136:139], off offset:1024
	global_store_dwordx4 v[2:3], v[140:143], off offset:2048
	global_store_dwordx4 v[2:3], v[144:147], off offset:3072
	s_and_b64 vcc, exec, s[8:9]
	s_cbranch_vccz .Ln11_nohs_A
	global_store_dwordx2 v[10:11], v[180:181], off
	global_store_dwordx2 v[10:11], v[182:183], off offset:512
	global_store_dwordx2 v[10:11], v[184:185], off offset:1024
	global_store_dwordx2 v[10:11], v[186:187], off offset:1536
.Ln11_nohs_A:
	s_and_b64 vcc, exec, s[18:19]
	s_cbranch_vccz .Ln11_skipBs
	global_store_dwordx4 v[6:7], v[156:159], off
	global_store_dwordx4 v[6:7], v[160:163], off offset:1024
	global_store_dwordx4 v[6:7], v[164:167], off offset:2048
	global_store_dwordx4 v[6:7], v[168:171], off offset:3072
	s_and_b64 vcc, exec, s[8:9]
	s_cbranch_vccz .Ln11_nohs_B
	global_store_dwordx2 v[12:13], v[188:189], off
	global_store_dwordx2 v[12:13], v[190:191], off offset:512
	global_store_dwordx2 v[12:13], v[192:193], off offset:1024
	global_store_dwordx2 v[12:13], v[194:195], off offset:1536
.Ln11_nohs_B:
.Ln11_skipBs:
	s_add_i32 s22, s12, s70
	s_cmp_lt_i32 s22, 0x8000
	s_cbranch_scc1 .Ln11_loop
